# FFN-up epilogue: gelu chains as packed f32 pairs (v_pk_fma/v_pk_mul/v_pk_add, same per-element operations, bit-identical); weight-DMA setup without persistent SGPRs
# baseline (speedup 1.0000x reference)
; #define PG8_STAGE(bufoff, gbase, voff) do { _Pragma("unroll") for (int _i = 0; _i < 2; ++_i) \
;         __builtin_amdgcn_global_load_lds((const unsigned*)((const char*)(gbase) + (voff)[_i]), (PG8_LAS unsigned*)(lds + (bufoff) + ldsw + _i * 8192), 16, 0, 0); } while (0)
; #define PG8_WAIT_V(n) asm volatile("s_waitcnt vmcnt(" #n ")" ::: "memory")
; #define PG8_BAR __builtin_amdgcn_s_barrier()
; template <class Epi, class Sched, bool ALIGN_EPI = false, bool SP2 = false, bool AROWS128 = false>
; __device__ __forceinline__ void gemm_phase(PG8_LAS unsigned char* lds, const Gemm g, const Sched& S, const Epi& E) {
;     int tid_ = threadIdx.x; asm volatile("" : "+v"(tid_)); const int tid = tid_, wid = __builtin_amdgcn_readfirstlane(tid >> 6), lane = tid & 63, wr = wid >> 2, wc = wid & 3, fr = lane & 15, fq = lane >> 4;
;     const int K = g.K, nt = K / BK;
;     unsigned voffA[2], voffB[2];
; #pragma unroll
;     for (int i = 0; i < 2; ++i) { int R, C; stage_rc(tid * 16 + i * 8192, R, C); const int Rb = Epi::PERM ? ((R & ~31) + perm32(R & 31)) : R;
;         const int Ra = AROWS128 ? (128 * (R >> 6) + (R & 63)) : R;
;         voffA[i] = (unsigned)(Ra * K + C) * 2u; voffB[i] = (unsigned)(Rb * K + C) * 2u; }
;     const size_t kstep = (size_t)(BK * 2);
;     const size_t hstep = (size_t)HALF * K * 2;
;     const size_t tstep = 2 * hstep;
;     const size_t hstepA = AROWS128 ? hstep / 2 : hstep;
;     const unsigned ldsw = (unsigned)wid * 1024u;
;     const int aoff = lds_byte(wr * 64 + fr, fq * 8), boff = lds_byte(wc * 32 + fr, fq * 8);
;     ...
;         PG8_STAGE(PG8_SB(0, 0), cB, voffB); PG8_STAGE(PG8_SB(0, 1), cB + hstep, voffB); PG8_STAGE(PG8_SA(0, 0), cA, voffA); PG8_STAGE(PG8_SA(0, 1), cA + hstepA, voffA);
;         if (wr == 1) PG8_BAR;
;         PG8_WAIT_V(2); PG8_BAR;
;         PG8_STAGE(PG8_SB(1, 0), cB + kstep, voffB); PG8_STAGE(PG8_SA(1, 0), cA + kstep, voffA); PG8_STAGE(PG8_SB(1, 1), cB + hstep + kstep, voffB);
;         PG8_WAIT_V(6); PG8_BAR;
.LBB0_620:
	s_lshl_b32 s0, s0, 5
	s_mov_b64 s[26:27], 0x80
	s_and_b32 s14, s0, 0x60
	s_add_i32 m0, s84, 0x18000
	v_lshl_add_u64 v[6:7], v[6:7], 0, s[26:27]
	s_lshl_b32 s4, s12, 13
	s_lshl_b32 s5, s14, 7
	s_waitcnt vmcnt(2)
	s_barrier
	global_load_lds_dwordx4 v[6:7], off
	v_lshl_add_u64 v[4:5], v[4:5], 0, s[26:27]
	s_add_i32 m0, s84, 0x1a000
	s_add_i32 s89, s84, 0x8000
	s_add_i32 s90, s84, 0xa000
	global_load_lds_dwordx4 v[4:5], off
	v_lshl_add_u64 v[0:1], v[0:1], 0, s[26:27]
	s_mov_b32 m0, s89
	s_add_u32 s0, s20, 0x40080
	global_load_lds_dwordx4 v[0:1], off
	v_lshl_add_u64 v[0:1], v[2:3], 0, s[26:27]
	s_mov_b32 m0, s90
	s_addc_u32 s1, s21, 0
	global_load_lds_dwordx4 v[0:1], off
	s_add_i32 m0, s84, 0x1c000
	v_lshl_add_u64 v[0:1], s[0:1], 0, v[162:163]
	global_load_lds_dwordx4 v[0:1], off
	v_lshl_add_u64 v[0:1], s[0:1], 0, v[166:167]
	s_add_i32 m0, s84, 0x1e000
	v_lshlrev_b32_e32 v3, 2, v8
	global_load_lds_dwordx4 v[0:1], off
	v_and_b32_e32 v0, 15, v8
	v_lshrrev_b32_e32 v1, 1, v8
	v_and_b32_e32 v1, 24, v1
	v_lshlrev_b32_e32 v2, 6, v0
	v_lshl_or_b32 v2, v1, 1, v2
	v_and_b32_e32 v3, 32, v3
	v_bitop3_b32 v4, v2, s4, v3 bitop3:0xde
	v_bitop3_b32 v200, v2, s5, v3 bitop3:0xde
	v_and_b32_e32 v2, 3, v8
	v_lshl_or_b32 v201, s12, 7, v0
	v_cmp_eq_u32_e64 s[0:1], 15, v0
	v_cmp_eq_u32_e64 s[4:5], 0, v0
	v_cmp_eq_u32_e64 s[6:7], 1, v2
	v_cmp_eq_u32_e64 s[8:9], 2, v2
	v_add_u32_e32 v2, -1, v2
	v_cmp_ne_u32_e64 s[10:11], 15, v0
	v_cmp_gt_u32_e64 s[12:13], 4, v0
	v_cmp_ne_u32_e64 s[36:37], 0, v0
	v_lshlrev_b32_e32 v0, 5, v201
	s_cmpk_lt_u32 s3, 0x100
	v_cmp_gt_u32_e64 s[30:31], 2, v2
	v_add_u32_e32 v203, 0xffe80000, v0
	v_add_u32_e32 v205, 0xffe80800, v0
	v_lshlrev_b32_e32 v0, 11, v11
	v_and_b32_e32 v2, 1, v9
	s_cselect_b64 s[28:29], -1, 0
	s_ashr_i32 s92, s74, 31
	s_ashr_i32 s94, s2, 31
	v_or_b32_e32 v206, s14, v1
	v_and_b32_e32 v0, 0xfffc0000, v0
	v_lshlrev_b32_e32 v1, 11, v12
	v_lshlrev_b32_e32 v2, 6, v2
	s_add_u32 s38, s60, 0x4000
	v_or3_b32 v0, v0, v1, v2
	s_addc_u32 s39, s61, 0
	v_lshl_add_u32 v168, v10, 1, v0
	v_lshlrev_b32_e32 v0, 11, v15
	v_and_b32_e32 v2, 1, v13
	s_waitcnt vmcnt(6)
	s_add_u32 s50, s60, 0x8000
	v_and_b32_e32 v0, 0xfffc0000, v0
	v_lshlrev_b32_e32 v1, 11, v16
	v_lshlrev_b32_e32 v2, 6, v2
	s_addc_u32 s51, s61, 0
	v_or3_b32 v0, v0, v1, v2
	s_add_i32 s3, 0, 0x10000
	s_add_i32 s95, 0, 0x14000
	s_movk_i32 s91, 0x100
	s_mov_b32 s93, s74
	v_add_u32_e32 v202, 0xffff4000, v201
	v_add_u32_e32 v204, 0xffff4040, v201
	v_mov_b32_e32 v169, v163
	v_lshl_add_u32 v170, v14, 1, v0
	v_mov_b32_e32 v171, v163
	v_mov_b64_e32 v[172:173], 0x18c0
	v_mov_b64_e32 v[174:175], 0x18bf
	v_add_u32_e32 v207, s3, v200
	v_add_u32_e32 v208, s95, v200
	v_add_u32_e32 v209, 0, v4
	s_mov_b32 s96, 0x2aaaaaab
	s_mov_b32 s97, 0x3d372713
	v_mbcnt_lo_u32_b32 v232, -1, 0
	v_mbcnt_hi_u32_b32 v232, -1, v232
	v_and_b32_e32 v233, 7, v232
	v_lshlrev_b32_e32 v233, 4, v233
	v_lshrrev_b32_e32 v235, 5, v206
	v_lshl_add_u32 v233, v235, 7, v233
	v_bfe_u32 v235, v232, 3, 2
	v_mov_b32_e32 v230, s60
	v_mov_b32_e32 v231, s61
	v_cmp_eq_u32_e32 vcc, 1, v235
	v_mov_b32_e32 v236, s38
	v_mov_b32_e32 v237, s39
	v_cndmask_b32_e32 v230, v230, v236, vcc
	v_cndmask_b32_e32 v231, v231, v237, vcc
	v_cmp_eq_u32_e32 vcc, 2, v235
	v_mov_b32_e32 v236, s50
	v_mov_b32_e32 v237, s51
	v_cndmask_b32_e32 v230, v230, v236, vcc
	v_cndmask_b32_e32 v231, v231, v237, vcc
	v_cmp_eq_u32_e32 vcc, 3, v235
	v_mov_b32_e32 v236, s62
	v_mov_b32_e32 v237, s63
	v_cndmask_b32_e32 v230, v230, v236, vcc
	v_cndmask_b32_e32 v231, v231, v237, vcc
	v_mov_b32_e32 v236, v233
	v_mov_b32_e32 v237, 0
	v_lshl_add_u64 v[230:231], v[230:231], 0, v[236:237]
	s_lshr_b32 s98, s84, 1
	s_add_i32 s98, s98, 0x21000
	v_bfe_u32 v234, v206, 3, 2
	v_lshlrev_b32_e32 v234, 5, v234
	v_add_u32_e32 v234, s98, v234
	s_mov_b32 s98, 0x3d372713
	s_mov_b32 s99, 1.0
	s_mov_b32 s100, 0xc0135761
	s_barrier
	s_branch .LBB0_623

;     __device__ __forceinline__ void operator()(const f32x4 (&acc)[2][2][4][2], const Unit& u, int wr, int wc, int fr, int fq) const {
;     ...
;         for (int n = 0; n < 2; ++n) { w0[n] = *(const f32x4*)(cw + ch0 + 4 * n); w1[n] = *(const f32x4*)(cw + 4096 + ch0 + 4 * n); w2[n] = *(const f32x4*)(cw + 8192 + ch0 + 4 * n); bb[n] = *(const f32x4*)(cb + ch0 + 4 * n); }
; template <class Epi, class Sched, bool ALIGN_EPI = false, bool SP2 = false, bool AROWS128 = false>
; __device__ __forceinline__ void gemm_phase(PG8_LAS unsigned char* lds, const Gemm g, const Sched& S, const Epi& E) {
;     ...
; #pragma unroll
;         for (int a = 0; a < 2; ++a)
; #pragma unroll
;             for (int b = 0; b < 2; ++b)
; #pragma unroll
;                 for (int m = 0; m < 4; ++m)
; #pragma unroll
;                     for (int n = 0; n < 2; ++n) acc[a][b][m][n] = (f32x4){0.f, 0.f, 0.f, 0.f};
;         cur = nxt; cA = nA; cB = nB; ++ui;
.LBB0_625:
	v_mov_b32_e32 v236, s16
	v_lshlrev_b32_e32 v236, 9, v236
	v_mov_b32_e32 v237, 0
	v_lshl_add_u64 v[232:233], v[230:231], 0, v[236:237]
	s_lshr_b32 m0, s84, 1
	s_add_i32 m0, m0, 0x21000
	s_mov_b32 exec_hi, 0
	global_load_lds_dwordx4 v[232:233], off
	s_mov_b32 exec_hi, -1
	s_ashr_i32 s55, s54, 31
	s_lshl_b64 s[56:57], s[54:55], 19
	s_add_u32 s56, s46, s56
	s_addc_u32 s57, s47, s57
	s_and_b64 s[58:59], s[14:15], exec
	s_cselect_b32 s17, s57, s19
	s_cselect_b32 s33, s56, s18
	s_ashr_i32 s53, s52, 31
	s_lshl_b64 s[58:59], s[52:53], 19
	s_add_u32 s58, s78, s58
	s_addc_u32 s59, s79, s59
	s_and_b64 s[72:73], s[14:15], exec
	s_cselect_b32 s53, s59, s21
	s_cselect_b32 s55, s58, s20
	s_add_u32 s18, s18, 0x20080
	s_addc_u32 s19, s19, 0
	s_add_u32 s65, s20, 0x100
	v_mov_b32_e32 v0, 0
	s_addc_u32 s72, s21, 0
	s_mov_b32 s73, -2
	v_mov_b64_e32 v[0:1], 0
	v_mov_b64_e32 v[2:3], 0
	v_mov_b64_e32 v[4:5], 0
	v_mov_b64_e32 v[6:7], 0
	v_mov_b64_e32 v[8:9], 0
	v_mov_b64_e32 v[10:11], 0
	v_mov_b64_e32 v[12:13], 0
	v_mov_b64_e32 v[14:15], 0
	v_mov_b64_e32 v[16:17], 0
	v_mov_b64_e32 v[18:19], 0
	v_mov_b64_e32 v[20:21], 0
	v_mov_b64_e32 v[22:23], 0
	v_mov_b64_e32 v[24:25], 0
	v_mov_b64_e32 v[26:27], 0
	v_mov_b64_e32 v[28:29], 0
	v_mov_b64_e32 v[30:31], 0
	v_mov_b64_e32 v[32:33], 0
	v_mov_b64_e32 v[34:35], 0
	v_mov_b64_e32 v[36:37], 0
	v_mov_b64_e32 v[38:39], 0
	v_mov_b64_e32 v[40:41], 0
	v_mov_b64_e32 v[42:43], 0
	v_mov_b64_e32 v[44:45], 0
	v_mov_b64_e32 v[46:47], 0
	v_mov_b64_e32 v[48:49], 0
	v_mov_b64_e32 v[50:51], 0
	v_mov_b64_e32 v[52:53], 0
	v_mov_b64_e32 v[54:55], 0
	v_mov_b64_e32 v[56:57], 0
	v_mov_b64_e32 v[58:59], 0
	v_mov_b64_e32 v[60:61], 0
	v_mov_b64_e32 v[62:63], 0
	v_mov_b64_e32 v[64:65], 0
	v_mov_b64_e32 v[66:67], 0
	v_mov_b64_e32 v[68:69], 0
	v_mov_b64_e32 v[70:71], 0
	v_mov_b64_e32 v[104:105], 0
	v_mov_b64_e32 v[106:107], 0
	v_mov_b64_e32 v[108:109], 0
	v_mov_b64_e32 v[110:111], 0
	v_mov_b64_e32 v[112:113], 0
	v_mov_b64_e32 v[114:115], 0
	v_mov_b64_e32 v[116:117], 0
	v_mov_b64_e32 v[118:119], 0
	v_mov_b64_e32 v[120:121], 0
	v_mov_b64_e32 v[122:123], 0
	v_mov_b64_e32 v[124:125], 0
	v_mov_b64_e32 v[126:127], 0
	v_mov_b64_e32 v[128:129], 0
	v_mov_b64_e32 v[130:131], 0
	v_mov_b64_e32 v[132:133], 0
	v_mov_b64_e32 v[134:135], 0
	v_mov_b64_e32 v[136:137], 0
	v_mov_b64_e32 v[138:139], 0
	v_mov_b64_e32 v[140:141], 0
	v_mov_b64_e32 v[142:143], 0
	v_mov_b64_e32 v[144:145], 0
	v_mov_b64_e32 v[146:147], 0
	v_mov_b64_e32 v[148:149], 0
	v_mov_b64_e32 v[150:151], 0
	v_mov_b64_e32 v[152:153], 0
	v_mov_b64_e32 v[154:155], 0
	v_mov_b64_e32 v[156:157], 0
	v_mov_b64_e32 v[158:159], 0

; __device__ __forceinline__ float dpp_ror1(float v) { return __builtin_bit_cast(float, __builtin_amdgcn_update_dpp(0, __builtin_bit_cast(int, v), 0x121, 0xf, 0xf, false)); }
; __device__ __forceinline__ float dpp_ror15(float v) { return __builtin_bit_cast(float, __builtin_amdgcn_update_dpp(0, __builtin_bit_cast(int, v), 0x12F, 0xf, 0xf, false)); }
;     __device__ __forceinline__ void operator()(const f32x4 (&acc)[2][2][4][2], const Unit& u, int wr, int wc, int fr, int fq) const {
;     ...
;                     for (int j = 0; j < 4; ++j) { gp[j] = dpp_ror1(tp[j]); gn[j] = dpp_ror15(tn[j]); }
;                     const f32x4 cv = (w0[n] * fzp) * gp + (w1[n] * g + ((w2[n] * fzn) * gn + bb[n]));
;                     const f32x4 inner = cv * (cv * cv * 0.044715f + 1.0f) * (-2.0f * 0.7978845608028654f * 1.4426950408889634f);
;                     f32x4 sg;
; #pragma unroll
;                     for (int j = 0; j < 4; ++j) sg[j] = __builtin_amdgcn_rcpf(1.0f + __builtin_amdgcn_exp2f(inner[j]));
;                     res[n] = cv * sg * up;
.LBB0_631:
	s_and_b64 s[16:17], s[0:1], s[18:19]
	s_and_b64 s[18:19], s[4:5], s[18:19]
	v_cndmask_b32_e64 v188, v36, v140, s[18:19]
	v_cndmask_b32_e64 v184, v36, v12, s[16:17]
	v_cndmask_b32_e64 v185, v39, v143, s[18:19]
	v_cndmask_b32_e64 v186, v38, v142, s[18:19]
	v_cndmask_b32_e64 v187, v37, v141, s[18:19]
	v_mov_b32_dpp v196, v188 row_ror:15 row_mask:0xf bank_mask:0xf
	v_cndmask_b32_e64 v189, v28, v136, s[18:19]
	v_cndmask_b32_e64 v179, v39, v15, s[16:17]
	v_cndmask_b32_e64 v181, v38, v14, s[16:17]
	v_cndmask_b32_e64 v183, v37, v13, s[16:17]
	v_mov_b32_dpp v192, v184 row_ror:1 row_mask:0xf bank_mask:0xf
	v_mov_b32_dpp v197, v187 row_ror:15 row_mask:0xf bank_mask:0xf
	v_mov_b32_dpp v198, v186 row_ror:15 row_mask:0xf bank_mask:0xf
	v_mov_b32_dpp v199, v185 row_ror:15 row_mask:0xf bank_mask:0xf
	v_cndmask_b32_e64 v185, v28, v8, s[16:17]
	v_cndmask_b32_e64 v187, v30, v138, s[18:19]
	v_cndmask_b32_e64 v186, v29, v137, s[18:19]
	v_mov_b32_dpp v188, v189 row_ror:15 row_mask:0xf bank_mask:0xf
	v_mov_b32_dpp v193, v183 row_ror:1 row_mask:0xf bank_mask:0xf
	v_mov_b32_dpp v194, v181 row_ror:1 row_mask:0xf bank_mask:0xf
	v_mov_b32_dpp v195, v179 row_ror:1 row_mask:0xf bank_mask:0xf
	v_cndmask_b32_e64 v179, v31, v11, s[16:17]
	v_cndmask_b32_e64 v181, v30, v10, s[16:17]
	v_cndmask_b32_e64 v183, v29, v9, s[16:17]
	v_cndmask_b32_e64 v212, v31, v139, s[18:19]
	v_mov_b32_dpp v184, v185 row_ror:1 row_mask:0xf bank_mask:0xf
	v_mov_b32_dpp v189, v186 row_ror:15 row_mask:0xf bank_mask:0xf
	v_mov_b32_dpp v190, v187 row_ror:15 row_mask:0xf bank_mask:0xf
	v_mov_b32_dpp v185, v183 row_ror:1 row_mask:0xf bank_mask:0xf
	v_mov_b32_dpp v186, v181 row_ror:1 row_mask:0xf bank_mask:0xf
	v_mov_b32_dpp v187, v179 row_ror:1 row_mask:0xf bank_mask:0xf
	v_mov_b32_dpp v191, v212 row_ror:15 row_mask:0xf bank_mask:0xf
	s_waitcnt lgkmcnt(0)
	s_and_saveexec_b64 s[20:21], s[82:83]
	s_cbranch_execz .LBB0_633
	v_pk_mul_f32 v[218:219], v[96:97], v[180:181] op_sel_hi:[1,0]
	v_pk_mul_f32 v[214:215], v[88:89], v[182:183] op_sel_hi:[1,0]
	v_pk_fma_f32 v[196:197], v[218:219], v[196:197], v[100:101]
	v_pk_mul_f32 v[216:217], v[98:99], v[180:181] op_sel_hi:[1,0]
	v_pk_fma_f32 v[196:197], v[36:37], v[92:93], v[196:197]
	v_pk_fma_f32 v[198:199], v[216:217], v[198:199], v[102:103]
	v_pk_fma_f32 v[192:193], v[214:215], v[192:193], v[196:197]
	v_pk_mul_f32 v[212:213], v[90:91], v[182:183] op_sel_hi:[1,0]
	v_pk_mul_f32 v[196:197], v[192:193], v[192:193]
	v_pk_fma_f32 v[238:239], v[196:197], s[98:99], s[98:99] op_sel:[0,0,1] op_sel_hi:[1,0,1]
	v_pk_mul_f32 v[238:239], v[192:193], v[238:239]
	v_pk_mul_f32 v[238:239], v[238:239], s[100:101] op_sel_hi:[1,0]
	v_exp_f32_e32 v238, v238
	v_exp_f32_e32 v239, v239
	v_pk_fma_f32 v[198:199], v[38:39], v[94:95], v[198:199]
	v_pk_add_f32 v[238:239], v[238:239], s[98:99] op_sel:[0,1] op_sel_hi:[1,1]
	v_pk_fma_f32 v[194:195], v[212:213], v[194:195], v[198:199]
	v_pk_mul_f32 v[198:199], v[194:195], v[194:195]
	v_pk_fma_f32 v[240:241], v[198:199], s[98:99], s[98:99] op_sel:[0,0,1] op_sel_hi:[1,0,1]
	v_pk_mul_f32 v[240:241], v[194:195], v[240:241]
	v_pk_mul_f32 v[240:241], v[240:241], s[100:101] op_sel_hi:[1,0]
	v_exp_f32_e32 v240, v240
	v_exp_f32_e32 v241, v241
	v_rcp_f32_e32 v196, v238
	v_pk_add_f32 v[240:241], v[240:241], s[98:99] op_sel:[0,1] op_sel_hi:[1,1]
	v_rcp_f32_e32 v198, v240
	v_rcp_f32_e32 v199, v241
	v_rcp_f32_e32 v197, v239
	v_pk_mul_f32 v[194:195], v[194:195], v[198:199]
	v_pk_mul_f32 v[198:199], v[82:83], v[180:181] op_sel_hi:[1,0]
	v_pk_mul_f32 v[180:181], v[80:81], v[180:181] op_sel_hi:[1,0]
	v_pk_mul_f32 v[192:193], v[192:193], v[196:197]
	v_pk_fma_f32 v[180:181], v[180:181], v[188:189], v[84:85]
	v_pk_mul_f32 v[196:197], v[74:75], v[182:183] op_sel_hi:[1,0]
	v_pk_mul_f32 v[182:183], v[72:73], v[182:183] op_sel_hi:[1,0]
	v_pk_fma_f32 v[180:181], v[28:29], v[76:77], v[180:181]
	v_pk_fma_f32 v[190:191], v[198:199], v[190:191], v[86:87]
	v_pk_fma_f32 v[180:181], v[182:183], v[184:185], v[180:181]
	v_pk_fma_f32 v[184:185], v[30:31], v[78:79], v[190:191]
	v_pk_mul_f32 v[182:183], v[180:181], v[180:181]
	v_pk_fma_f32 v[242:243], v[182:183], s[98:99], s[98:99] op_sel:[0,0,1] op_sel_hi:[1,0,1]
	v_pk_mul_f32 v[242:243], v[180:181], v[242:243]
	v_pk_mul_f32 v[242:243], v[242:243], s[100:101] op_sel_hi:[1,0]
	v_exp_f32_e32 v242, v242
	v_exp_f32_e32 v243, v243
	v_pk_fma_f32 v[184:185], v[196:197], v[186:187], v[184:185]
	v_pk_add_f32 v[242:243], v[242:243], s[98:99] op_sel:[0,1] op_sel_hi:[1,1]
	v_pk_mul_f32 v[186:187], v[184:185], v[184:185]
	v_pk_fma_f32 v[244:245], v[186:187], s[98:99], s[98:99] op_sel:[0,0,1] op_sel_hi:[1,0,1]
	v_pk_mul_f32 v[244:245], v[184:185], v[244:245]
	v_pk_mul_f32 v[244:245], v[244:245], s[100:101] op_sel_hi:[1,0]
	v_exp_f32_e32 v244, v244
	v_exp_f32_e32 v245, v245
	v_pk_mul_f32 v[156:157], v[156:157], v[192:193]
	v_pk_add_f32 v[244:245], v[244:245], s[98:99] op_sel:[0,1] op_sel_hi:[1,1]
	v_pk_mul_f32 v[158:159], v[158:159], v[194:195]
	v_rcp_f32_e32 v182, v242
	v_rcp_f32_e32 v186, v244
	v_rcp_f32_e32 v187, v245
	v_rcp_f32_e32 v183, v243
	v_ashrrev_i32_e32 v179, 31, v178
	v_pk_mul_f32 v[184:185], v[184:185], v[186:187]
	v_pk_mul_f32 v[180:181], v[180:181], v[182:183]
	v_pk_mul_f32 v[182:183], v[154:155], v[184:185]
	v_pk_mul_f32 v[154:155], v[152:153], v[180:181]
	v_cvt_pk_bf16_f32 v152, v156, v157
	v_lshlrev_b64 v[156:157], 13, v[178:179]
	v_lshl_add_u64 v[156:157], s[44:45], 0, v[156:157]
	v_lshl_add_u64 v[156:157], v[176:177], 1, v[156:157]
	v_cvt_pk_bf16_f32 v153, v158, v159
	v_cvt_pk_bf16_f32 v154, v154, v155
	v_cvt_pk_bf16_f32 v155, v182, v183
	global_store_dwordx4 v[156:157], v[152:155], off nt

; __device__ __forceinline__ unsigned cvt_pk_bf16(float lo, float hi) { unsigned r; asm volatile("v_cvt_pk_bf16_f32 %0, %1, %2" : "=v"(r) : "v"(lo), "v"(hi)); return r; }
; __device__ __forceinline__ float dpp_ror1(float v) { return __builtin_bit_cast(float, __builtin_amdgcn_update_dpp(0, __builtin_bit_cast(int, v), 0x121, 0xf, 0xf, false)); }
; __device__ __forceinline__ float dpp_ror15(float v) { return __builtin_bit_cast(float, __builtin_amdgcn_update_dpp(0, __builtin_bit_cast(int, v), 0x12F, 0xf, 0xf, false)); }
;     __device__ __forceinline__ void operator()(const f32x4 (&acc)[2][2][4][2], const Unit& u, int wr, int wc, int fr, int fq) const {
;     ...
;                 f32x4 res[2];
;                 const float fzp = zp ? 0.f : 1.f, fzn = zn ? 0.f : 1.f;
; #pragma unroll
;                 for (int n = 0; n < 2; ++n) {
;                     const f32x4 g = acc[ai][0][m][n], up = acc[ai][1][m][n];
;                     f32x4 tp = g, tn = g;
;                     if (!fix) { const f32x4 gm = (m > 0) ? acc[ai][0][m - 1][n] : acc[ai ^ 1][0][3][n], gx = (m < 3) ? acc[ai][0][m + 1][n] : acc[ai ^ 1][0][0][n];
;                         tp = (fr == 15) ? gm : g; tn = (fr == 0) ? gx : g; }
;                     f32x4 gp, gn;
; #pragma unroll
;                     for (int j = 0; j < 4; ++j) { gp[j] = dpp_ror1(tp[j]); gn[j] = dpp_ror15(tn[j]); }
;                     const f32x4 cv = (w0[n] * fzp) * gp + (w1[n] * g + ((w2[n] * fzn) * gn + bb[n]));
;                     const f32x4 inner = cv * (cv * cv * 0.044715f + 1.0f) * (-2.0f * 0.7978845608028654f * 1.4426950408889634f);
;                     f32x4 sg;
; #pragma unroll
;                     for (int j = 0; j < 4; ++j) sg[j] = __builtin_amdgcn_rcpf(1.0f + __builtin_amdgcn_exp2f(inner[j]));
;                     res[n] = cv * sg * up;
;                 }
;                 if (valid) { u32x4 w; w.x = cvt_pk_bf16(res[0][0], res[0][1]); w.y = cvt_pk_bf16(res[0][2], res[0][3]); w.z = cvt_pk_bf16(res[1][0], res[1][1]); w.w = cvt_pk_bf16(res[1][2], res[1][3]);
;                     __builtin_nontemporal_store(w, (u32x4*)(ACT + (size_t)grow * 4096 + ch0)); }
.LBB0_639:
	v_cndmask_b32_e64 v154, v142, v38, s[16:17]
	v_cndmask_b32_e64 v155, v141, v37, s[16:17]
	v_cndmask_b32_e64 v158, v142, v126, s[18:19]
	v_cndmask_b32_e64 v159, v141, v125, s[18:19]
	v_cndmask_b32_e64 v156, v140, v36, s[16:17]
	v_cndmask_b32_e64 v178, v140, v124, s[18:19]
	v_mov_b32_dpp v181, v155 row_ror:1 row_mask:0xf bank_mask:0xf
	v_mov_b32_dpp v185, v159 row_ror:15 row_mask:0xf bank_mask:0xf
	v_mov_b32_dpp v182, v154 row_ror:1 row_mask:0xf bank_mask:0xf
	v_mov_b32_dpp v186, v158 row_ror:15 row_mask:0xf bank_mask:0xf
	v_cndmask_b32_e64 v155, v136, v28, s[16:17]
	v_cndmask_b32_e64 v159, v136, v120, s[18:19]
	v_cndmask_b32_e64 v157, v143, v127, s[18:19]
	v_mov_b32_dpp v180, v156 row_ror:1 row_mask:0xf bank_mask:0xf
	v_mov_b32_dpp v184, v178 row_ror:15 row_mask:0xf bank_mask:0xf
	v_cndmask_b32_e64 v156, v137, v29, s[16:17]
	v_cndmask_b32_e64 v178, v137, v121, s[18:19]
	v_mov_b32_dpp v154, v155 row_ror:1 row_mask:0xf bank_mask:0xf
	v_mov_b32_dpp v158, v159 row_ror:15 row_mask:0xf bank_mask:0xf
	v_cndmask_b32_e64 v153, v143, v39, s[16:17]
	v_mov_b32_dpp v187, v157 row_ror:15 row_mask:0xf bank_mask:0xf
	v_cndmask_b32_e64 v157, v138, v30, s[16:17]
	v_cndmask_b32_e64 v179, v138, v122, s[18:19]
	v_mov_b32_dpp v155, v156 row_ror:1 row_mask:0xf bank_mask:0xf
	v_mov_b32_dpp v159, v178 row_ror:15 row_mask:0xf bank_mask:0xf
	v_mov_b32_dpp v183, v153 row_ror:1 row_mask:0xf bank_mask:0xf
	v_cndmask_b32_e64 v153, v139, v31, s[16:17]
	v_cndmask_b32_e64 v189, v139, v123, s[18:19]
	v_mov_b32_dpp v156, v157 row_ror:1 row_mask:0xf bank_mask:0xf
	v_mov_b32_dpp v178, v179 row_ror:15 row_mask:0xf bank_mask:0xf
	s_nop 0
	v_mov_b32_dpp v157, v153 row_ror:1 row_mask:0xf bank_mask:0xf
	v_mov_b32_dpp v179, v189 row_ror:15 row_mask:0xf bank_mask:0xf
	s_and_saveexec_b64 s[80:81], s[82:83]
	s_cbranch_execz .LBB0_641
	v_pk_fma_f32 v[184:185], v[96:97], v[184:185], v[100:101]
	v_pk_fma_f32 v[186:187], v[98:99], v[186:187], v[102:103]
	v_pk_fma_f32 v[184:185], v[140:141], v[92:93], v[184:185]
	v_pk_fma_f32 v[186:187], v[142:143], v[94:95], v[186:187]
	v_pk_fma_f32 v[180:181], v[88:89], v[180:181], v[184:185]
	v_pk_fma_f32 v[182:183], v[90:91], v[182:183], v[186:187]
	v_pk_mul_f32 v[184:185], v[180:181], v[180:181]
	v_pk_fma_f32 v[238:239], v[184:185], s[98:99], s[98:99] op_sel:[0,0,1] op_sel_hi:[1,0,1]
	v_pk_mul_f32 v[238:239], v[180:181], v[238:239]
	v_pk_mul_f32 v[238:239], v[238:239], s[100:101] op_sel_hi:[1,0]
	v_exp_f32_e32 v238, v238
	v_exp_f32_e32 v239, v239
	v_pk_mul_f32 v[186:187], v[182:183], v[182:183]
	v_pk_add_f32 v[238:239], v[238:239], s[98:99] op_sel:[0,1] op_sel_hi:[1,1]
	v_pk_fma_f32 v[240:241], v[186:187], s[98:99], s[98:99] op_sel:[0,0,1] op_sel_hi:[1,0,1]
	v_pk_mul_f32 v[240:241], v[182:183], v[240:241]
	v_pk_mul_f32 v[240:241], v[240:241], s[100:101] op_sel_hi:[1,0]
	v_exp_f32_e32 v240, v240
	v_exp_f32_e32 v241, v241
	v_pk_fma_f32 v[158:159], v[80:81], v[158:159], v[84:85]
	v_pk_add_f32 v[240:241], v[240:241], s[98:99] op_sel:[0,1] op_sel_hi:[1,1]
	v_pk_fma_f32 v[178:179], v[82:83], v[178:179], v[86:87]
	v_pk_fma_f32 v[158:159], v[136:137], v[76:77], v[158:159]
	v_rcp_f32_e32 v184, v238
	v_pk_fma_f32 v[154:155], v[72:73], v[154:155], v[158:159]
	v_rcp_f32_e32 v186, v240
	v_pk_mul_f32 v[158:159], v[154:155], v[154:155]
	v_pk_fma_f32 v[242:243], v[158:159], s[98:99], s[98:99] op_sel:[0,0,1] op_sel_hi:[1,0,1]
	v_pk_mul_f32 v[242:243], v[154:155], v[242:243]
	v_pk_mul_f32 v[242:243], v[242:243], s[100:101] op_sel_hi:[1,0]
	v_exp_f32_e32 v242, v242
	v_exp_f32_e32 v243, v243
	v_rcp_f32_e32 v187, v241
	v_rcp_f32_e32 v185, v239
	v_pk_fma_f32 v[178:179], v[138:139], v[78:79], v[178:179]
	v_pk_add_f32 v[242:243], v[242:243], s[98:99] op_sel:[0,1] op_sel_hi:[1,1]
	v_pk_mul_f32 v[180:181], v[180:181], v[184:185]
	v_pk_fma_f32 v[156:157], v[74:75], v[156:157], v[178:179]
	v_pk_mul_f32 v[178:179], v[156:157], v[156:157]
	v_pk_fma_f32 v[244:245], v[178:179], s[98:99], s[98:99] op_sel:[0,0,1] op_sel_hi:[1,0,1]
	v_pk_mul_f32 v[244:245], v[156:157], v[244:245]
	v_pk_mul_f32 v[244:245], v[244:245], s[100:101] op_sel_hi:[1,0]
	v_exp_f32_e32 v244, v244
	v_exp_f32_e32 v245, v245
	v_rcp_f32_e32 v158, v242
	v_pk_add_f32 v[244:245], v[244:245], s[98:99] op_sel:[0,1] op_sel_hi:[1,1]
	v_rcp_f32_e32 v178, v244
	v_rcp_f32_e32 v179, v245
	v_rcp_f32_e32 v159, v243
	v_pk_mul_f32 v[148:149], v[148:149], v[180:181]
	v_ashrrev_i32_e32 v153, 31, v152
	v_pk_mul_f32 v[156:157], v[156:157], v[178:179]
	v_pk_mul_f32 v[154:155], v[154:155], v[158:159]
	v_pk_mul_f32 v[156:157], v[146:147], v[156:157]
	v_pk_mul_f32 v[146:147], v[144:145], v[154:155]
	v_cvt_pk_bf16_f32 v144, v148, v149
	v_lshlrev_b64 v[148:149], 13, v[152:153]
	v_lshl_add_u64 v[148:149], s[44:45], 0, v[148:149]
	v_pk_mul_f32 v[182:183], v[182:183], v[186:187]
	v_lshl_add_u64 v[148:149], v[176:177], 1, v[148:149]
	v_pk_mul_f32 v[150:151], v[150:151], v[182:183]
	s_nop 0
	v_cvt_pk_bf16_f32 v145, v150, v151
	v_cvt_pk_bf16_f32 v146, v146, v147
	v_cvt_pk_bf16_f32 v147, v156, v157
	global_store_dwordx4 v[148:149], v[144:147], off nt

; __device__ __forceinline__ unsigned cvt_pk_bf16(float lo, float hi) { unsigned r; asm volatile("v_cvt_pk_bf16_f32 %0, %1, %2" : "=v"(r) : "v"(lo), "v"(hi)); return r; }
; __device__ __forceinline__ float dpp_ror1(float v) { return __builtin_bit_cast(float, __builtin_amdgcn_update_dpp(0, __builtin_bit_cast(int, v), 0x121, 0xf, 0xf, false)); }
; __device__ __forceinline__ float dpp_ror15(float v) { return __builtin_bit_cast(float, __builtin_amdgcn_update_dpp(0, __builtin_bit_cast(int, v), 0x12F, 0xf, 0xf, false)); }
;     __device__ __forceinline__ void operator()(const f32x4 (&acc)[2][2][4][2], const Unit& u, int wr, int wc, int fr, int fq) const {
;     ...
;                 f32x4 res[2];
;                 const float fzp = zp ? 0.f : 1.f, fzn = zn ? 0.f : 1.f;
; #pragma unroll
;                 for (int n = 0; n < 2; ++n) {
;                     const f32x4 g = acc[ai][0][m][n], up = acc[ai][1][m][n];
;                     f32x4 tp = g, tn = g;
;                     if (!fix) { const f32x4 gm = (m > 0) ? acc[ai][0][m - 1][n] : acc[ai ^ 1][0][3][n], gx = (m < 3) ? acc[ai][0][m + 1][n] : acc[ai ^ 1][0][0][n];
;                         tp = (fr == 15) ? gm : g; tn = (fr == 0) ? gx : g; }
;                     f32x4 gp, gn;
; #pragma unroll
;                     for (int j = 0; j < 4; ++j) { gp[j] = dpp_ror1(tp[j]); gn[j] = dpp_ror15(tn[j]); }
;                     const f32x4 cv = (w0[n] * fzp) * gp + (w1[n] * g + ((w2[n] * fzn) * gn + bb[n]));
;                     const f32x4 inner = cv * (cv * cv * 0.044715f + 1.0f) * (-2.0f * 0.7978845608028654f * 1.4426950408889634f);
;                     f32x4 sg;
; #pragma unroll
;                     for (int j = 0; j < 4; ++j) sg[j] = __builtin_amdgcn_rcpf(1.0f + __builtin_amdgcn_exp2f(inner[j]));
;                     res[n] = cv * sg * up;
;                 }
;                 if (valid) { u32x4 w; w.x = cvt_pk_bf16(res[0][0], res[0][1]); w.y = cvt_pk_bf16(res[0][2], res[0][3]); w.z = cvt_pk_bf16(res[1][0], res[1][1]); w.w = cvt_pk_bf16(res[1][2], res[1][3]);
;                     __builtin_nontemporal_store(w, (u32x4*)(ACT + (size_t)grow * 4096 + ch0)); }
.LBB0_647:
	v_cndmask_b32_e64 v149, v126, v110, s[18:19]
	v_cndmask_b32_e64 v143, v127, v143, s[16:17]
	v_cndmask_b32_e64 v147, v124, v108, s[18:19]
	v_mov_b32_dpp v152, v149 row_ror:15 row_mask:0xf bank_mask:0xf
	v_cndmask_b32_e64 v141, v125, v141, s[16:17]
	v_mov_b32_dpp v149, v143 row_ror:1 row_mask:0xf bank_mask:0xf
	v_cndmask_b32_e64 v143, v123, v139, s[16:17]
	v_cndmask_b32_e64 v139, v122, v138, s[16:17]
	v_cndmask_b32_e64 v138, v121, v137, s[16:17]
	v_cndmask_b32_e64 v137, v120, v136, s[16:17]
	v_cndmask_b32_e64 v140, v124, v140, s[16:17]
	v_cndmask_b32_e64 v148, v125, v109, s[18:19]
	v_mov_b32_dpp v150, v147 row_ror:15 row_mask:0xf bank_mask:0xf
	v_mov_b32_dpp v136, v137 row_ror:1 row_mask:0xf bank_mask:0xf
	v_cndmask_b32_e64 v142, v126, v142, s[16:17]
	v_mov_b32_dpp v146, v140 row_ror:1 row_mask:0xf bank_mask:0xf
	v_mov_b32_dpp v147, v141 row_ror:1 row_mask:0xf bank_mask:0xf
	v_mov_b32_dpp v151, v148 row_ror:15 row_mask:0xf bank_mask:0xf
	v_cndmask_b32_e64 v141, v120, v104, s[18:19]
	v_mov_b32_dpp v137, v138 row_ror:1 row_mask:0xf bank_mask:0xf
	v_cndmask_b32_e64 v145, v127, v111, s[18:19]
	v_mov_b32_dpp v148, v142 row_ror:1 row_mask:0xf bank_mask:0xf
	v_cndmask_b32_e64 v142, v121, v105, s[18:19]
	v_mov_b32_dpp v140, v141 row_ror:15 row_mask:0xf bank_mask:0xf
	v_mov_b32_dpp v138, v139 row_ror:1 row_mask:0xf bank_mask:0xf
	v_mov_b32_dpp v153, v145 row_ror:15 row_mask:0xf bank_mask:0xf
	v_cndmask_b32_e64 v145, v123, v107, s[18:19]
	v_cndmask_b32_e64 v154, v122, v106, s[18:19]
	v_mov_b32_dpp v141, v142 row_ror:15 row_mask:0xf bank_mask:0xf
	v_mov_b32_dpp v139, v143 row_ror:1 row_mask:0xf bank_mask:0xf
	v_mov_b32_dpp v142, v154 row_ror:15 row_mask:0xf bank_mask:0xf
	s_nop 0
	v_mov_b32_dpp v143, v145 row_ror:15 row_mask:0xf bank_mask:0xf
	s_and_saveexec_b64 s[80:81], s[82:83]
	s_cbranch_execz .LBB0_649
	v_pk_fma_f32 v[150:151], v[96:97], v[150:151], v[100:101]
	v_pk_fma_f32 v[152:153], v[98:99], v[152:153], v[102:103]
	v_pk_fma_f32 v[150:151], v[124:125], v[92:93], v[150:151]
	v_pk_fma_f32 v[152:153], v[126:127], v[94:95], v[152:153]
	v_pk_fma_f32 v[146:147], v[88:89], v[146:147], v[150:151]
	v_pk_fma_f32 v[148:149], v[90:91], v[148:149], v[152:153]
	v_pk_mul_f32 v[150:151], v[146:147], v[146:147]
	v_pk_fma_f32 v[238:239], v[150:151], s[98:99], s[98:99] op_sel:[0,0,1] op_sel_hi:[1,0,1]
	v_pk_mul_f32 v[238:239], v[146:147], v[238:239]
	v_pk_mul_f32 v[238:239], v[238:239], s[100:101] op_sel_hi:[1,0]
	v_exp_f32_e32 v238, v238
	v_exp_f32_e32 v239, v239
	v_pk_fma_f32 v[142:143], v[82:83], v[142:143], v[86:87]
	v_pk_add_f32 v[238:239], v[238:239], s[98:99] op_sel:[0,1] op_sel_hi:[1,1]
	v_pk_fma_f32 v[140:141], v[80:81], v[140:141], v[84:85]
	v_pk_mul_f32 v[152:153], v[148:149], v[148:149]
	v_pk_fma_f32 v[240:241], v[152:153], s[98:99], s[98:99] op_sel:[0,0,1] op_sel_hi:[1,0,1]
	v_pk_mul_f32 v[240:241], v[148:149], v[240:241]
	v_pk_mul_f32 v[240:241], v[240:241], s[100:101] op_sel_hi:[1,0]
	v_exp_f32_e32 v240, v240
	v_exp_f32_e32 v241, v241
	v_pk_fma_f32 v[140:141], v[120:121], v[76:77], v[140:141]
	v_pk_add_f32 v[240:241], v[240:241], s[98:99] op_sel:[0,1] op_sel_hi:[1,1]
	v_pk_fma_f32 v[142:143], v[122:123], v[78:79], v[142:143]
	v_rcp_f32_e32 v150, v238
	v_pk_fma_f32 v[136:137], v[72:73], v[136:137], v[140:141]
	v_pk_fma_f32 v[138:139], v[74:75], v[138:139], v[142:143]
	v_pk_mul_f32 v[140:141], v[136:137], v[136:137]
	v_pk_fma_f32 v[242:243], v[140:141], s[98:99], s[98:99] op_sel:[0,0,1] op_sel_hi:[1,0,1]
	v_pk_mul_f32 v[242:243], v[136:137], v[242:243]
	v_pk_mul_f32 v[242:243], v[242:243], s[100:101] op_sel_hi:[1,0]
	v_exp_f32_e32 v242, v242
	v_exp_f32_e32 v243, v243
	v_pk_mul_f32 v[142:143], v[138:139], v[138:139]
	v_pk_add_f32 v[242:243], v[242:243], s[98:99] op_sel:[0,1] op_sel_hi:[1,1]
	v_pk_fma_f32 v[244:245], v[142:143], s[98:99], s[98:99] op_sel:[0,0,1] op_sel_hi:[1,0,1]
	v_pk_mul_f32 v[244:245], v[138:139], v[244:245]
	v_pk_mul_f32 v[244:245], v[244:245], s[100:101] op_sel_hi:[1,0]
	v_exp_f32_e32 v244, v244
	v_exp_f32_e32 v245, v245
	v_rcp_f32_e32 v152, v240
	v_rcp_f32_e32 v153, v241
	v_rcp_f32_e32 v151, v239
	v_rcp_f32_e32 v140, v242
	v_pk_add_f32 v[244:245], v[244:245], s[98:99] op_sel:[0,1] op_sel_hi:[1,1]
	v_rcp_f32_e32 v142, v244
	v_rcp_f32_e32 v143, v245
	v_rcp_f32_e32 v141, v243
	v_pk_mul_f32 v[146:147], v[146:147], v[150:151]
	v_ashrrev_i32_e32 v145, 31, v144
	v_pk_mul_f32 v[132:133], v[132:133], v[146:147]
	v_pk_mul_f32 v[138:139], v[138:139], v[142:143]
	v_pk_mul_f32 v[136:137], v[136:137], v[140:141]
	v_pk_mul_f32 v[138:139], v[130:131], v[138:139]
	v_pk_mul_f32 v[130:131], v[128:129], v[136:137]
	v_cvt_pk_bf16_f32 v128, v132, v133
	v_lshlrev_b64 v[132:133], 13, v[144:145]
	v_lshl_add_u64 v[132:133], s[44:45], 0, v[132:133]
	v_pk_mul_f32 v[148:149], v[148:149], v[152:153]
	v_lshl_add_u64 v[132:133], v[176:177], 1, v[132:133]
	v_pk_mul_f32 v[134:135], v[134:135], v[148:149]
	s_nop 0
	v_cvt_pk_bf16_f32 v129, v134, v135
	v_cvt_pk_bf16_f32 v130, v130, v131
	v_cvt_pk_bf16_f32 v131, v138, v139
	global_store_dwordx4 v[132:133], v[128:131], off nt

; __device__ __forceinline__ unsigned cvt_pk_bf16(float lo, float hi) { unsigned r; asm volatile("v_cvt_pk_bf16_f32 %0, %1, %2" : "=v"(r) : "v"(lo), "v"(hi)); return r; }
; __device__ __forceinline__ float dpp_ror1(float v) { return __builtin_bit_cast(float, __builtin_amdgcn_update_dpp(0, __builtin_bit_cast(int, v), 0x121, 0xf, 0xf, false)); }
; __device__ __forceinline__ float dpp_ror15(float v) { return __builtin_bit_cast(float, __builtin_amdgcn_update_dpp(0, __builtin_bit_cast(int, v), 0x12F, 0xf, 0xf, false)); }
;     __device__ __forceinline__ void operator()(const f32x4 (&acc)[2][2][4][2], const Unit& u, int wr, int wc, int fr, int fq) const {
;     ...
;                 f32x4 res[2];
;                 const float fzp = zp ? 0.f : 1.f, fzn = zn ? 0.f : 1.f;
; #pragma unroll
;                 for (int n = 0; n < 2; ++n) {
;                     const f32x4 g = acc[ai][0][m][n], up = acc[ai][1][m][n];
;                     f32x4 tp = g, tn = g;
;                     if (!fix) { const f32x4 gm = (m > 0) ? acc[ai][0][m - 1][n] : acc[ai ^ 1][0][3][n], gx = (m < 3) ? acc[ai][0][m + 1][n] : acc[ai ^ 1][0][0][n];
;                         tp = (fr == 15) ? gm : g; tn = (fr == 0) ? gx : g; }
;                     f32x4 gp, gn;
; #pragma unroll
;                     for (int j = 0; j < 4; ++j) { gp[j] = dpp_ror1(tp[j]); gn[j] = dpp_ror15(tn[j]); }
;                     const f32x4 cv = (w0[n] * fzp) * gp + (w1[n] * g + ((w2[n] * fzn) * gn + bb[n]));
;                     const f32x4 inner = cv * (cv * cv * 0.044715f + 1.0f) * (-2.0f * 0.7978845608028654f * 1.4426950408889634f);
;                     f32x4 sg;
; #pragma unroll
;                     for (int j = 0; j < 4; ++j) sg[j] = __builtin_amdgcn_rcpf(1.0f + __builtin_amdgcn_exp2f(inner[j]));
;                     res[n] = cv * sg * up;
;                 }
;                 if (valid) { u32x4 w; w.x = cvt_pk_bf16(res[0][0], res[0][1]); w.y = cvt_pk_bf16(res[0][2], res[0][3]); w.z = cvt_pk_bf16(res[1][0], res[1][1]); w.w = cvt_pk_bf16(res[1][2], res[1][3]);
;                     __builtin_nontemporal_store(w, (u32x4*)(ACT + (size_t)grow * 4096 + ch0)); }
.LBB0_655:
	v_cndmask_b32_e64 v133, v110, v62, s[18:19]
	v_cndmask_b32_e64 v127, v111, v127, s[16:17]
	v_cndmask_b32_e64 v131, v108, v60, s[18:19]
	v_mov_b32_dpp v136, v133 row_ror:15 row_mask:0xf bank_mask:0xf
	v_cndmask_b32_e64 v125, v109, v125, s[16:17]
	v_mov_b32_dpp v133, v127 row_ror:1 row_mask:0xf bank_mask:0xf
	v_cndmask_b32_e64 v127, v107, v123, s[16:17]
	v_cndmask_b32_e64 v123, v106, v122, s[16:17]
	v_cndmask_b32_e64 v122, v105, v121, s[16:17]
	v_cndmask_b32_e64 v121, v104, v120, s[16:17]
	v_cndmask_b32_e64 v124, v108, v124, s[16:17]
	v_cndmask_b32_e64 v132, v109, v61, s[18:19]
	v_mov_b32_dpp v134, v131 row_ror:15 row_mask:0xf bank_mask:0xf
	v_mov_b32_dpp v120, v121 row_ror:1 row_mask:0xf bank_mask:0xf
	v_cndmask_b32_e64 v126, v110, v126, s[16:17]
	v_mov_b32_dpp v130, v124 row_ror:1 row_mask:0xf bank_mask:0xf
	v_mov_b32_dpp v131, v125 row_ror:1 row_mask:0xf bank_mask:0xf
	v_mov_b32_dpp v135, v132 row_ror:15 row_mask:0xf bank_mask:0xf
	v_cndmask_b32_e64 v125, v104, v56, s[18:19]
	v_mov_b32_dpp v121, v122 row_ror:1 row_mask:0xf bank_mask:0xf
	v_cndmask_b32_e64 v129, v111, v63, s[18:19]
	v_mov_b32_dpp v132, v126 row_ror:1 row_mask:0xf bank_mask:0xf
	v_cndmask_b32_e64 v126, v105, v57, s[18:19]
	v_mov_b32_dpp v124, v125 row_ror:15 row_mask:0xf bank_mask:0xf
	v_mov_b32_dpp v122, v123 row_ror:1 row_mask:0xf bank_mask:0xf
	v_mov_b32_dpp v137, v129 row_ror:15 row_mask:0xf bank_mask:0xf
	v_cndmask_b32_e64 v129, v107, v59, s[18:19]
	v_cndmask_b32_e64 v138, v106, v58, s[18:19]
	v_mov_b32_dpp v125, v126 row_ror:15 row_mask:0xf bank_mask:0xf
	v_mov_b32_dpp v123, v127 row_ror:1 row_mask:0xf bank_mask:0xf
	v_mov_b32_dpp v126, v138 row_ror:15 row_mask:0xf bank_mask:0xf
	s_nop 0
	v_mov_b32_dpp v127, v129 row_ror:15 row_mask:0xf bank_mask:0xf
	s_and_saveexec_b64 s[80:81], s[82:83]
	s_cbranch_execz .LBB0_657
	v_pk_fma_f32 v[134:135], v[96:97], v[134:135], v[100:101]
	v_pk_fma_f32 v[136:137], v[98:99], v[136:137], v[102:103]
	v_pk_fma_f32 v[134:135], v[108:109], v[92:93], v[134:135]
	v_pk_fma_f32 v[136:137], v[110:111], v[94:95], v[136:137]
	v_pk_fma_f32 v[130:131], v[88:89], v[130:131], v[134:135]
	v_pk_fma_f32 v[132:133], v[90:91], v[132:133], v[136:137]
	v_pk_mul_f32 v[134:135], v[130:131], v[130:131]
	v_pk_fma_f32 v[238:239], v[134:135], s[98:99], s[98:99] op_sel:[0,0,1] op_sel_hi:[1,0,1]
	v_pk_mul_f32 v[238:239], v[130:131], v[238:239]
	v_pk_mul_f32 v[238:239], v[238:239], s[100:101] op_sel_hi:[1,0]
	v_exp_f32_e32 v238, v238
	v_exp_f32_e32 v239, v239
	v_pk_fma_f32 v[126:127], v[82:83], v[126:127], v[86:87]
	v_pk_add_f32 v[238:239], v[238:239], s[98:99] op_sel:[0,1] op_sel_hi:[1,1]
	v_pk_fma_f32 v[124:125], v[80:81], v[124:125], v[84:85]
	v_pk_mul_f32 v[136:137], v[132:133], v[132:133]
	v_pk_fma_f32 v[240:241], v[136:137], s[98:99], s[98:99] op_sel:[0,0,1] op_sel_hi:[1,0,1]
	v_pk_mul_f32 v[240:241], v[132:133], v[240:241]
	v_pk_mul_f32 v[240:241], v[240:241], s[100:101] op_sel_hi:[1,0]
	v_exp_f32_e32 v240, v240
	v_exp_f32_e32 v241, v241
	v_pk_fma_f32 v[124:125], v[104:105], v[76:77], v[124:125]
	v_pk_add_f32 v[240:241], v[240:241], s[98:99] op_sel:[0,1] op_sel_hi:[1,1]
	v_pk_fma_f32 v[126:127], v[106:107], v[78:79], v[126:127]
	v_rcp_f32_e32 v134, v238
	v_pk_fma_f32 v[120:121], v[72:73], v[120:121], v[124:125]
	v_pk_fma_f32 v[122:123], v[74:75], v[122:123], v[126:127]
	v_pk_mul_f32 v[124:125], v[120:121], v[120:121]
	v_pk_fma_f32 v[242:243], v[124:125], s[98:99], s[98:99] op_sel:[0,0,1] op_sel_hi:[1,0,1]
	v_pk_mul_f32 v[242:243], v[120:121], v[242:243]
	v_pk_mul_f32 v[242:243], v[242:243], s[100:101] op_sel_hi:[1,0]
	v_exp_f32_e32 v242, v242
	v_exp_f32_e32 v243, v243
	v_pk_mul_f32 v[126:127], v[122:123], v[122:123]
	v_pk_add_f32 v[242:243], v[242:243], s[98:99] op_sel:[0,1] op_sel_hi:[1,1]
	v_pk_fma_f32 v[244:245], v[126:127], s[98:99], s[98:99] op_sel:[0,0,1] op_sel_hi:[1,0,1]
	v_pk_mul_f32 v[244:245], v[122:123], v[244:245]
	v_pk_mul_f32 v[244:245], v[244:245], s[100:101] op_sel_hi:[1,0]
	v_exp_f32_e32 v244, v244
	v_exp_f32_e32 v245, v245
	v_rcp_f32_e32 v136, v240
	v_rcp_f32_e32 v137, v241
	v_rcp_f32_e32 v135, v239
	v_rcp_f32_e32 v124, v242
	v_pk_add_f32 v[244:245], v[244:245], s[98:99] op_sel:[0,1] op_sel_hi:[1,1]
	v_rcp_f32_e32 v126, v244
	v_rcp_f32_e32 v127, v245
	v_rcp_f32_e32 v125, v243
	v_pk_mul_f32 v[130:131], v[130:131], v[134:135]
	v_ashrrev_i32_e32 v129, 31, v128
	v_pk_mul_f32 v[116:117], v[116:117], v[130:131]
	v_pk_mul_f32 v[122:123], v[122:123], v[126:127]
	v_pk_mul_f32 v[120:121], v[120:121], v[124:125]
	v_pk_mul_f32 v[122:123], v[114:115], v[122:123]
	v_pk_mul_f32 v[114:115], v[112:113], v[120:121]
	v_cvt_pk_bf16_f32 v112, v116, v117
	v_lshlrev_b64 v[116:117], 13, v[128:129]
	v_lshl_add_u64 v[116:117], s[44:45], 0, v[116:117]
	v_pk_mul_f32 v[132:133], v[132:133], v[136:137]
	v_lshl_add_u64 v[116:117], v[176:177], 1, v[116:117]
	v_pk_mul_f32 v[118:119], v[118:119], v[132:133]
	s_nop 0
	v_cvt_pk_bf16_f32 v113, v118, v119
	v_cvt_pk_bf16_f32 v114, v114, v115
	v_cvt_pk_bf16_f32 v115, v122, v123
	global_store_dwordx4 v[116:117], v[112:115], off nt

; __device__ __forceinline__ unsigned cvt_pk_bf16(float lo, float hi) { unsigned r; asm volatile("v_cvt_pk_bf16_f32 %0, %1, %2" : "=v"(r) : "v"(lo), "v"(hi)); return r; }
; __device__ __forceinline__ float dpp_ror1(float v) { return __builtin_bit_cast(float, __builtin_amdgcn_update_dpp(0, __builtin_bit_cast(int, v), 0x121, 0xf, 0xf, false)); }
; __device__ __forceinline__ float dpp_ror15(float v) { return __builtin_bit_cast(float, __builtin_amdgcn_update_dpp(0, __builtin_bit_cast(int, v), 0x12F, 0xf, 0xf, false)); }
;     __device__ __forceinline__ void operator()(const f32x4 (&acc)[2][2][4][2], const Unit& u, int wr, int wc, int fr, int fq) const {
;     ...
;                 f32x4 res[2];
;                 const float fzp = zp ? 0.f : 1.f, fzn = zn ? 0.f : 1.f;
; #pragma unroll
;                 for (int n = 0; n < 2; ++n) {
;                     const f32x4 g = acc[ai][0][m][n], up = acc[ai][1][m][n];
;                     f32x4 tp = g, tn = g;
;                     if (!fix) { const f32x4 gm = (m > 0) ? acc[ai][0][m - 1][n] : acc[ai ^ 1][0][3][n], gx = (m < 3) ? acc[ai][0][m + 1][n] : acc[ai ^ 1][0][0][n];
;                         tp = (fr == 15) ? gm : g; tn = (fr == 0) ? gx : g; }
;                     f32x4 gp, gn;
; #pragma unroll
;                     for (int j = 0; j < 4; ++j) { gp[j] = dpp_ror1(tp[j]); gn[j] = dpp_ror15(tn[j]); }
;                     const f32x4 cv = (w0[n] * fzp) * gp + (w1[n] * g + ((w2[n] * fzn) * gn + bb[n]));
;                     const f32x4 inner = cv * (cv * cv * 0.044715f + 1.0f) * (-2.0f * 0.7978845608028654f * 1.4426950408889634f);
;                     f32x4 sg;
; #pragma unroll
;                     for (int j = 0; j < 4; ++j) sg[j] = __builtin_amdgcn_rcpf(1.0f + __builtin_amdgcn_exp2f(inner[j]));
;                     res[n] = cv * sg * up;
;                 }
;                 if (valid) { u32x4 w; w.x = cvt_pk_bf16(res[0][0], res[0][1]); w.y = cvt_pk_bf16(res[0][2], res[0][3]); w.z = cvt_pk_bf16(res[1][0], res[1][1]); w.w = cvt_pk_bf16(res[1][2], res[1][3]);
;                     __builtin_nontemporal_store(w, (u32x4*)(ACT + (size_t)grow * 4096 + ch0)); }
.LBB0_661:
	v_cndmask_b32_e64 v111, v63, v111, s[16:17]
	v_cndmask_b32_e64 v119, v60, v44, s[18:19]
	v_mov_b32_e32 v122, 0
	v_mov_b32_dpp v121, v111 row_ror:1 row_mask:0xf bank_mask:0xf
	v_cndmask_b32_e64 v111, v59, v107, s[16:17]
	v_cndmask_b32_e64 v107, v58, v106, s[16:17]
	v_cndmask_b32_e64 v106, v57, v105, s[16:17]
	v_cndmask_b32_e64 v105, v56, v104, s[16:17]
	v_cndmask_b32_e64 v109, v61, v109, s[16:17]
	v_cndmask_b32_e64 v108, v60, v108, s[16:17]
	v_mov_b32_dpp v122, v119 row_ror:15 row_mask:0xf bank_mask:0xf
	v_mov_b32_dpp v104, v105 row_ror:1 row_mask:0xf bank_mask:0xf
	v_cndmask_b32_e64 v110, v62, v110, s[16:17]
	v_mov_b32_dpp v118, v108 row_ror:1 row_mask:0xf bank_mask:0xf
	v_mov_b32_dpp v119, v109 row_ror:1 row_mask:0xf bank_mask:0xf
	v_cndmask_b32_e64 v109, v56, v40, s[18:19]
	v_mov_b32_dpp v105, v106 row_ror:1 row_mask:0xf bank_mask:0xf
	v_cndmask_b32_e64 v113, v63, v47, s[18:19]
	v_cndmask_b32_e64 v115, v62, v46, s[18:19]
	v_mov_b32_dpp v120, v110 row_ror:1 row_mask:0xf bank_mask:0xf
	v_cndmask_b32_e64 v110, v57, v41, s[18:19]
	v_mov_b32_dpp v108, v109 row_ror:15 row_mask:0xf bank_mask:0xf
	v_mov_b32_dpp v106, v107 row_ror:1 row_mask:0xf bank_mask:0xf
	v_cndmask_b32_e64 v117, v61, v45, s[18:19]
	v_mov_b32_dpp v124, v115 row_ror:15 row_mask:0xf bank_mask:0xf
	v_mov_b32_dpp v125, v113 row_ror:15 row_mask:0xf bank_mask:0xf
	v_cndmask_b32_e64 v113, v59, v43, s[18:19]
	v_cndmask_b32_e64 v115, v58, v42, s[18:19]
	v_mov_b32_dpp v109, v110 row_ror:15 row_mask:0xf bank_mask:0xf
	v_mov_b32_dpp v107, v111 row_ror:1 row_mask:0xf bank_mask:0xf
	v_mov_b32_dpp v123, v117 row_ror:15 row_mask:0xf bank_mask:0xf
	v_mov_b32_dpp v110, v115 row_ror:15 row_mask:0xf bank_mask:0xf
	v_mov_b32_dpp v111, v113 row_ror:15 row_mask:0xf bank_mask:0xf
	s_and_saveexec_b64 s[80:81], s[82:83]
	s_cbranch_execz .LBB0_663
	v_pk_mul_f32 v[132:133], v[96:97], v[114:115] op_sel_hi:[1,0]
	v_pk_mul_f32 v[128:129], v[88:89], v[116:117] op_sel_hi:[1,0]
	v_pk_fma_f32 v[122:123], v[132:133], v[122:123], v[100:101]
	v_pk_mul_f32 v[130:131], v[98:99], v[114:115] op_sel_hi:[1,0]
	v_pk_fma_f32 v[122:123], v[60:61], v[92:93], v[122:123]
	v_pk_fma_f32 v[124:125], v[130:131], v[124:125], v[102:103]
	v_pk_fma_f32 v[118:119], v[128:129], v[118:119], v[122:123]
	v_pk_mul_f32 v[126:127], v[90:91], v[116:117] op_sel_hi:[1,0]
	v_pk_mul_f32 v[122:123], v[118:119], v[118:119]
	v_pk_fma_f32 v[238:239], v[122:123], s[98:99], s[98:99] op_sel:[0,0,1] op_sel_hi:[1,0,1]
	v_pk_mul_f32 v[238:239], v[118:119], v[238:239]
	v_pk_mul_f32 v[238:239], v[238:239], s[100:101] op_sel_hi:[1,0]
	v_exp_f32_e32 v238, v238
	v_exp_f32_e32 v239, v239
	v_pk_fma_f32 v[124:125], v[62:63], v[94:95], v[124:125]
	v_pk_add_f32 v[238:239], v[238:239], s[98:99] op_sel:[0,1] op_sel_hi:[1,1]
	v_pk_fma_f32 v[120:121], v[126:127], v[120:121], v[124:125]
	v_pk_mul_f32 v[124:125], v[120:121], v[120:121]
	v_pk_fma_f32 v[240:241], v[124:125], s[98:99], s[98:99] op_sel:[0,0,1] op_sel_hi:[1,0,1]
	v_pk_mul_f32 v[240:241], v[120:121], v[240:241]
	v_pk_mul_f32 v[240:241], v[240:241], s[100:101] op_sel_hi:[1,0]
	v_exp_f32_e32 v240, v240
	v_exp_f32_e32 v241, v241
	v_rcp_f32_e32 v122, v238
	v_pk_add_f32 v[240:241], v[240:241], s[98:99] op_sel:[0,1] op_sel_hi:[1,1]
	v_rcp_f32_e32 v124, v240
	v_rcp_f32_e32 v125, v241
	v_rcp_f32_e32 v123, v239
	v_ashrrev_i32_e32 v113, 31, v112
	v_pk_mul_f32 v[120:121], v[120:121], v[124:125]
	v_pk_mul_f32 v[124:125], v[82:83], v[114:115] op_sel_hi:[1,0]
	v_pk_mul_f32 v[114:115], v[80:81], v[114:115] op_sel_hi:[1,0]
	v_pk_fma_f32 v[110:111], v[124:125], v[110:111], v[86:87]
	v_pk_fma_f32 v[108:109], v[114:115], v[108:109], v[84:85]
	v_pk_mul_f32 v[118:119], v[118:119], v[122:123]
	v_pk_mul_f32 v[122:123], v[74:75], v[116:117] op_sel_hi:[1,0]
	v_pk_mul_f32 v[116:117], v[72:73], v[116:117] op_sel_hi:[1,0]
	v_pk_fma_f32 v[108:109], v[56:57], v[76:77], v[108:109]
	v_pk_fma_f32 v[110:111], v[58:59], v[78:79], v[110:111]
	v_pk_fma_f32 v[104:105], v[116:117], v[104:105], v[108:109]
	v_pk_fma_f32 v[106:107], v[122:123], v[106:107], v[110:111]
	v_pk_mul_f32 v[108:109], v[104:105], v[104:105]
	v_pk_fma_f32 v[242:243], v[108:109], s[98:99], s[98:99] op_sel:[0,0,1] op_sel_hi:[1,0,1]
	v_pk_mul_f32 v[242:243], v[104:105], v[242:243]
	v_pk_mul_f32 v[242:243], v[242:243], s[100:101] op_sel_hi:[1,0]
	v_exp_f32_e32 v242, v242
	v_exp_f32_e32 v243, v243
	v_pk_mul_f32 v[110:111], v[106:107], v[106:107]
	v_pk_add_f32 v[242:243], v[242:243], s[98:99] op_sel:[0,1] op_sel_hi:[1,1]
	v_pk_fma_f32 v[244:245], v[110:111], s[98:99], s[98:99] op_sel:[0,0,1] op_sel_hi:[1,0,1]
	v_pk_mul_f32 v[244:245], v[106:107], v[244:245]
	v_pk_mul_f32 v[244:245], v[244:245], s[100:101] op_sel_hi:[1,0]
	v_exp_f32_e32 v244, v244
	v_exp_f32_e32 v245, v245
	v_rcp_f32_e32 v108, v242
	v_pk_add_f32 v[244:245], v[244:245], s[98:99] op_sel:[0,1] op_sel_hi:[1,1]
	v_rcp_f32_e32 v110, v244
	v_rcp_f32_e32 v111, v245
	v_rcp_f32_e32 v109, v243
	v_pk_mul_f32 v[68:69], v[68:69], v[118:119]
	v_pk_mul_f32 v[70:71], v[70:71], v[120:121]
	v_pk_mul_f32 v[106:107], v[106:107], v[110:111]
	v_pk_mul_f32 v[104:105], v[104:105], v[108:109]
	v_pk_mul_f32 v[106:107], v[66:67], v[106:107]
	v_pk_mul_f32 v[66:67], v[64:65], v[104:105]
	v_cvt_pk_bf16_f32 v64, v68, v69
	v_lshlrev_b64 v[68:69], 13, v[112:113]
	v_lshl_add_u64 v[68:69], s[44:45], 0, v[68:69]
	v_lshl_add_u64 v[68:69], v[176:177], 1, v[68:69]
	v_cvt_pk_bf16_f32 v65, v70, v71
	v_cvt_pk_bf16_f32 v66, v66, v67
	v_cvt_pk_bf16_f32 v67, v106, v107
	global_store_dwordx4 v[68:69], v[64:67], off nt

; __device__ __forceinline__ unsigned cvt_pk_bf16(float lo, float hi) { unsigned r; asm volatile("v_cvt_pk_bf16_f32 %0, %1, %2" : "=v"(r) : "v"(lo), "v"(hi)); return r; }
; __device__ __forceinline__ float dpp_ror1(float v) { return __builtin_bit_cast(float, __builtin_amdgcn_update_dpp(0, __builtin_bit_cast(int, v), 0x121, 0xf, 0xf, false)); }
; __device__ __forceinline__ float dpp_ror15(float v) { return __builtin_bit_cast(float, __builtin_amdgcn_update_dpp(0, __builtin_bit_cast(int, v), 0x12F, 0xf, 0xf, false)); }
;     __device__ __forceinline__ void operator()(const f32x4 (&acc)[2][2][4][2], const Unit& u, int wr, int wc, int fr, int fq) const {
;     ...
;                 f32x4 res[2];
;                 const float fzp = zp ? 0.f : 1.f, fzn = zn ? 0.f : 1.f;
; #pragma unroll
;                 for (int n = 0; n < 2; ++n) {
;                     const f32x4 g = acc[ai][0][m][n], up = acc[ai][1][m][n];
;                     f32x4 tp = g, tn = g;
;                     if (!fix) { const f32x4 gm = (m > 0) ? acc[ai][0][m - 1][n] : acc[ai ^ 1][0][3][n], gx = (m < 3) ? acc[ai][0][m + 1][n] : acc[ai ^ 1][0][0][n];
;                         tp = (fr == 15) ? gm : g; tn = (fr == 0) ? gx : g; }
;                     f32x4 gp, gn;
; #pragma unroll
;                     for (int j = 0; j < 4; ++j) { gp[j] = dpp_ror1(tp[j]); gn[j] = dpp_ror15(tn[j]); }
;                     const f32x4 cv = (w0[n] * fzp) * gp + (w1[n] * g + ((w2[n] * fzn) * gn + bb[n]));
;                     const f32x4 inner = cv * (cv * cv * 0.044715f + 1.0f) * (-2.0f * 0.7978845608028654f * 1.4426950408889634f);
;                     f32x4 sg;
; #pragma unroll
;                     for (int j = 0; j < 4; ++j) sg[j] = __builtin_amdgcn_rcpf(1.0f + __builtin_amdgcn_exp2f(inner[j]));
;                     res[n] = cv * sg * up;
;                 }
;                 if (valid) { u32x4 w; w.x = cvt_pk_bf16(res[0][0], res[0][1]); w.y = cvt_pk_bf16(res[0][2], res[0][3]); w.z = cvt_pk_bf16(res[1][0], res[1][1]); w.w = cvt_pk_bf16(res[1][2], res[1][3]);
;                     __builtin_nontemporal_store(w, (u32x4*)(ACT + (size_t)grow * 4096 + ch0)); }
.LBB0_669:
	v_cndmask_b32_e64 v69, v46, v22, s[18:19]
	v_cndmask_b32_e64 v63, v47, v63, s[16:17]
	v_cndmask_b32_e64 v67, v44, v20, s[18:19]
	v_mov_b32_dpp v104, v69 row_ror:15 row_mask:0xf bank_mask:0xf
	v_cndmask_b32_e64 v61, v45, v61, s[16:17]
	v_mov_b32_dpp v69, v63 row_ror:1 row_mask:0xf bank_mask:0xf
	v_cndmask_b32_e64 v63, v43, v59, s[16:17]
	v_cndmask_b32_e64 v59, v42, v58, s[16:17]
	v_cndmask_b32_e64 v58, v41, v57, s[16:17]
	v_cndmask_b32_e64 v57, v40, v56, s[16:17]
	v_cndmask_b32_e64 v60, v44, v60, s[16:17]
	v_cndmask_b32_e64 v68, v45, v21, s[18:19]
	v_mov_b32_dpp v70, v67 row_ror:15 row_mask:0xf bank_mask:0xf
	v_mov_b32_dpp v56, v57 row_ror:1 row_mask:0xf bank_mask:0xf
	v_cndmask_b32_e64 v62, v46, v62, s[16:17]
	v_mov_b32_dpp v66, v60 row_ror:1 row_mask:0xf bank_mask:0xf
	v_mov_b32_dpp v67, v61 row_ror:1 row_mask:0xf bank_mask:0xf
	v_mov_b32_dpp v71, v68 row_ror:15 row_mask:0xf bank_mask:0xf
	v_cndmask_b32_e64 v61, v40, v16, s[18:19]
	v_mov_b32_dpp v57, v58 row_ror:1 row_mask:0xf bank_mask:0xf
	v_cndmask_b32_e64 v65, v47, v23, s[18:19]
	v_mov_b32_dpp v68, v62 row_ror:1 row_mask:0xf bank_mask:0xf
	v_cndmask_b32_e64 v62, v41, v17, s[18:19]
	v_mov_b32_dpp v60, v61 row_ror:15 row_mask:0xf bank_mask:0xf
	v_mov_b32_dpp v58, v59 row_ror:1 row_mask:0xf bank_mask:0xf
	v_mov_b32_dpp v105, v65 row_ror:15 row_mask:0xf bank_mask:0xf
	v_cndmask_b32_e64 v65, v43, v19, s[18:19]
	v_cndmask_b32_e64 v107, v42, v18, s[18:19]
	v_mov_b32_dpp v61, v62 row_ror:15 row_mask:0xf bank_mask:0xf
	v_mov_b32_dpp v59, v63 row_ror:1 row_mask:0xf bank_mask:0xf
	v_mov_b32_dpp v62, v107 row_ror:15 row_mask:0xf bank_mask:0xf
	s_nop 0
	v_mov_b32_dpp v63, v65 row_ror:15 row_mask:0xf bank_mask:0xf
	s_and_saveexec_b64 s[64:65], s[80:81]
	s_cbranch_execz .LBB0_671
	v_pk_fma_f32 v[70:71], v[96:97], v[70:71], v[100:101]
	v_pk_fma_f32 v[104:105], v[98:99], v[104:105], v[102:103]
	v_pk_fma_f32 v[70:71], v[44:45], v[92:93], v[70:71]
	v_pk_fma_f32 v[104:105], v[46:47], v[94:95], v[104:105]
	v_pk_fma_f32 v[66:67], v[88:89], v[66:67], v[70:71]
	v_pk_fma_f32 v[68:69], v[90:91], v[68:69], v[104:105]
	v_pk_mul_f32 v[70:71], v[66:67], v[66:67]
	v_pk_fma_f32 v[238:239], v[70:71], s[98:99], s[98:99] op_sel:[0,0,1] op_sel_hi:[1,0,1]
	v_pk_mul_f32 v[238:239], v[66:67], v[238:239]
	v_pk_mul_f32 v[238:239], v[238:239], s[100:101] op_sel_hi:[1,0]
	v_exp_f32_e32 v238, v238
	v_exp_f32_e32 v239, v239
	v_pk_fma_f32 v[62:63], v[82:83], v[62:63], v[86:87]
	v_pk_add_f32 v[238:239], v[238:239], s[98:99] op_sel:[0,1] op_sel_hi:[1,1]
	v_pk_fma_f32 v[60:61], v[80:81], v[60:61], v[84:85]
	v_pk_mul_f32 v[104:105], v[68:69], v[68:69]
	v_pk_fma_f32 v[240:241], v[104:105], s[98:99], s[98:99] op_sel:[0,0,1] op_sel_hi:[1,0,1]
	v_pk_mul_f32 v[240:241], v[68:69], v[240:241]
	v_pk_mul_f32 v[240:241], v[240:241], s[100:101] op_sel_hi:[1,0]
	v_exp_f32_e32 v240, v240
	v_exp_f32_e32 v241, v241
	v_pk_fma_f32 v[60:61], v[40:41], v[76:77], v[60:61]
	v_pk_add_f32 v[240:241], v[240:241], s[98:99] op_sel:[0,1] op_sel_hi:[1,1]
	v_pk_fma_f32 v[62:63], v[42:43], v[78:79], v[62:63]
	v_rcp_f32_e32 v70, v238
	v_pk_fma_f32 v[56:57], v[72:73], v[56:57], v[60:61]
	v_pk_fma_f32 v[58:59], v[74:75], v[58:59], v[62:63]
	v_pk_mul_f32 v[60:61], v[56:57], v[56:57]
	v_pk_fma_f32 v[242:243], v[60:61], s[98:99], s[98:99] op_sel:[0,0,1] op_sel_hi:[1,0,1]
	v_pk_mul_f32 v[242:243], v[56:57], v[242:243]
	v_pk_mul_f32 v[242:243], v[242:243], s[100:101] op_sel_hi:[1,0]
	v_exp_f32_e32 v242, v242
	v_exp_f32_e32 v243, v243
	v_pk_mul_f32 v[62:63], v[58:59], v[58:59]
	v_pk_add_f32 v[242:243], v[242:243], s[98:99] op_sel:[0,1] op_sel_hi:[1,1]
	v_pk_fma_f32 v[244:245], v[62:63], s[98:99], s[98:99] op_sel:[0,0,1] op_sel_hi:[1,0,1]
	v_pk_mul_f32 v[244:245], v[58:59], v[244:245]
	v_pk_mul_f32 v[244:245], v[244:245], s[100:101] op_sel_hi:[1,0]
	v_exp_f32_e32 v244, v244
	v_exp_f32_e32 v245, v245
	v_rcp_f32_e32 v104, v240
	v_rcp_f32_e32 v105, v241
	v_rcp_f32_e32 v71, v239
	v_rcp_f32_e32 v60, v242
	v_pk_add_f32 v[244:245], v[244:245], s[98:99] op_sel:[0,1] op_sel_hi:[1,1]
	v_rcp_f32_e32 v62, v244
	v_rcp_f32_e32 v63, v245
	v_rcp_f32_e32 v61, v243
	v_pk_mul_f32 v[66:67], v[66:67], v[70:71]
	v_ashrrev_i32_e32 v65, 31, v64
	v_pk_mul_f32 v[52:53], v[52:53], v[66:67]
	v_pk_mul_f32 v[58:59], v[58:59], v[62:63]
	v_pk_mul_f32 v[56:57], v[56:57], v[60:61]
	v_pk_mul_f32 v[58:59], v[50:51], v[58:59]
	v_pk_mul_f32 v[50:51], v[48:49], v[56:57]
	v_cvt_pk_bf16_f32 v48, v52, v53
	v_lshlrev_b64 v[52:53], 13, v[64:65]
	v_lshl_add_u64 v[52:53], s[44:45], 0, v[52:53]
	v_pk_mul_f32 v[68:69], v[68:69], v[104:105]
	v_lshl_add_u64 v[52:53], v[176:177], 1, v[52:53]
	v_pk_mul_f32 v[54:55], v[54:55], v[68:69]
	s_nop 0
	v_cvt_pk_bf16_f32 v49, v54, v55
	v_cvt_pk_bf16_f32 v50, v50, v51
	v_cvt_pk_bf16_f32 v51, v58, v59
	global_store_dwordx4 v[52:53], v[48:51], off nt

; __device__ __forceinline__ unsigned cvt_pk_bf16(float lo, float hi) { unsigned r; asm volatile("v_cvt_pk_bf16_f32 %0, %1, %2" : "=v"(r) : "v"(lo), "v"(hi)); return r; }
; __device__ __forceinline__ float dpp_ror1(float v) { return __builtin_bit_cast(float, __builtin_amdgcn_update_dpp(0, __builtin_bit_cast(int, v), 0x121, 0xf, 0xf, false)); }
; __device__ __forceinline__ float dpp_ror15(float v) { return __builtin_bit_cast(float, __builtin_amdgcn_update_dpp(0, __builtin_bit_cast(int, v), 0x12F, 0xf, 0xf, false)); }
;     __device__ __forceinline__ void operator()(const f32x4 (&acc)[2][2][4][2], const Unit& u, int wr, int wc, int fr, int fq) const {
;     ...
;                 f32x4 res[2];
;                 const float fzp = zp ? 0.f : 1.f, fzn = zn ? 0.f : 1.f;
; #pragma unroll
;                 for (int n = 0; n < 2; ++n) {
;                     const f32x4 g = acc[ai][0][m][n], up = acc[ai][1][m][n];
;                     f32x4 tp = g, tn = g;
;                     if (!fix) { const f32x4 gm = (m > 0) ? acc[ai][0][m - 1][n] : acc[ai ^ 1][0][3][n], gx = (m < 3) ? acc[ai][0][m + 1][n] : acc[ai ^ 1][0][0][n];
;                         tp = (fr == 15) ? gm : g; tn = (fr == 0) ? gx : g; }
;                     f32x4 gp, gn;
; #pragma unroll
;                     for (int j = 0; j < 4; ++j) { gp[j] = dpp_ror1(tp[j]); gn[j] = dpp_ror15(tn[j]); }
;                     const f32x4 cv = (w0[n] * fzp) * gp + (w1[n] * g + ((w2[n] * fzn) * gn + bb[n]));
;                     const f32x4 inner = cv * (cv * cv * 0.044715f + 1.0f) * (-2.0f * 0.7978845608028654f * 1.4426950408889634f);
;                     f32x4 sg;
; #pragma unroll
;                     for (int j = 0; j < 4; ++j) sg[j] = __builtin_amdgcn_rcpf(1.0f + __builtin_amdgcn_exp2f(inner[j]));
;                     res[n] = cv * sg * up;
;                 }
;                 if (valid) { u32x4 w; w.x = cvt_pk_bf16(res[0][0], res[0][1]); w.y = cvt_pk_bf16(res[0][2], res[0][3]); w.z = cvt_pk_bf16(res[1][0], res[1][1]); w.w = cvt_pk_bf16(res[1][2], res[1][3]);
;                     __builtin_nontemporal_store(w, (u32x4*)(ACT + (size_t)grow * 4096 + ch0)); }
.LBB0_677:
	v_cndmask_b32_e64 v53, v22, v14, s[18:19]
	v_cndmask_b32_e64 v47, v23, v47, s[16:17]
	v_cndmask_b32_e64 v51, v20, v12, s[18:19]
	v_mov_b32_dpp v56, v53 row_ror:15 row_mask:0xf bank_mask:0xf
	v_cndmask_b32_e64 v45, v21, v45, s[16:17]
	v_mov_b32_dpp v53, v47 row_ror:1 row_mask:0xf bank_mask:0xf
	v_cndmask_b32_e64 v47, v19, v43, s[16:17]
	v_cndmask_b32_e64 v43, v18, v42, s[16:17]
	v_cndmask_b32_e64 v42, v17, v41, s[16:17]
	v_cndmask_b32_e64 v41, v16, v40, s[16:17]
	v_cndmask_b32_e64 v44, v20, v44, s[16:17]
	v_cndmask_b32_e64 v52, v21, v13, s[18:19]
	v_mov_b32_dpp v54, v51 row_ror:15 row_mask:0xf bank_mask:0xf
	v_mov_b32_dpp v40, v41 row_ror:1 row_mask:0xf bank_mask:0xf
	v_cndmask_b32_e64 v46, v22, v46, s[16:17]
	v_mov_b32_dpp v50, v44 row_ror:1 row_mask:0xf bank_mask:0xf
	v_mov_b32_dpp v51, v45 row_ror:1 row_mask:0xf bank_mask:0xf
	v_mov_b32_dpp v55, v52 row_ror:15 row_mask:0xf bank_mask:0xf
	v_cndmask_b32_e64 v45, v16, v8, s[18:19]
	v_mov_b32_dpp v41, v42 row_ror:1 row_mask:0xf bank_mask:0xf
	v_cndmask_b32_e64 v49, v23, v15, s[18:19]
	v_mov_b32_dpp v52, v46 row_ror:1 row_mask:0xf bank_mask:0xf
	v_cndmask_b32_e64 v46, v17, v9, s[18:19]
	v_mov_b32_dpp v44, v45 row_ror:15 row_mask:0xf bank_mask:0xf
	v_mov_b32_dpp v42, v43 row_ror:1 row_mask:0xf bank_mask:0xf
	v_mov_b32_dpp v57, v49 row_ror:15 row_mask:0xf bank_mask:0xf
	v_cndmask_b32_e64 v49, v19, v11, s[18:19]
	v_cndmask_b32_e64 v58, v18, v10, s[18:19]
	v_mov_b32_dpp v45, v46 row_ror:15 row_mask:0xf bank_mask:0xf
	v_mov_b32_dpp v43, v47 row_ror:1 row_mask:0xf bank_mask:0xf
	v_mov_b32_dpp v46, v58 row_ror:15 row_mask:0xf bank_mask:0xf
	s_nop 0
	v_mov_b32_dpp v47, v49 row_ror:15 row_mask:0xf bank_mask:0xf
	s_and_saveexec_b64 s[64:65], s[80:81]
	s_cbranch_execz .LBB0_679
	v_pk_fma_f32 v[54:55], v[96:97], v[54:55], v[100:101]
	v_pk_fma_f32 v[56:57], v[98:99], v[56:57], v[102:103]
	v_pk_fma_f32 v[54:55], v[20:21], v[92:93], v[54:55]
	v_pk_fma_f32 v[56:57], v[22:23], v[94:95], v[56:57]
	v_pk_fma_f32 v[50:51], v[88:89], v[50:51], v[54:55]
	v_pk_fma_f32 v[52:53], v[90:91], v[52:53], v[56:57]
	v_pk_mul_f32 v[54:55], v[50:51], v[50:51]
	v_pk_fma_f32 v[238:239], v[54:55], s[98:99], s[98:99] op_sel:[0,0,1] op_sel_hi:[1,0,1]
	v_pk_mul_f32 v[238:239], v[50:51], v[238:239]
	v_pk_mul_f32 v[238:239], v[238:239], s[100:101] op_sel_hi:[1,0]
	v_exp_f32_e32 v238, v238
	v_exp_f32_e32 v239, v239
	v_pk_fma_f32 v[46:47], v[82:83], v[46:47], v[86:87]
	v_pk_add_f32 v[238:239], v[238:239], s[98:99] op_sel:[0,1] op_sel_hi:[1,1]
	v_pk_fma_f32 v[44:45], v[80:81], v[44:45], v[84:85]
	v_pk_mul_f32 v[56:57], v[52:53], v[52:53]
	v_pk_fma_f32 v[240:241], v[56:57], s[98:99], s[98:99] op_sel:[0,0,1] op_sel_hi:[1,0,1]
	v_pk_mul_f32 v[240:241], v[52:53], v[240:241]
	v_pk_mul_f32 v[240:241], v[240:241], s[100:101] op_sel_hi:[1,0]
	v_exp_f32_e32 v240, v240
	v_exp_f32_e32 v241, v241
	v_pk_fma_f32 v[44:45], v[16:17], v[76:77], v[44:45]
	v_pk_add_f32 v[240:241], v[240:241], s[98:99] op_sel:[0,1] op_sel_hi:[1,1]
	v_pk_fma_f32 v[46:47], v[18:19], v[78:79], v[46:47]
	v_rcp_f32_e32 v54, v238
	v_pk_fma_f32 v[40:41], v[72:73], v[40:41], v[44:45]
	v_pk_fma_f32 v[42:43], v[74:75], v[42:43], v[46:47]
	v_pk_mul_f32 v[44:45], v[40:41], v[40:41]
	v_pk_fma_f32 v[242:243], v[44:45], s[98:99], s[98:99] op_sel:[0,0,1] op_sel_hi:[1,0,1]
	v_pk_mul_f32 v[242:243], v[40:41], v[242:243]
	v_pk_mul_f32 v[242:243], v[242:243], s[100:101] op_sel_hi:[1,0]
	v_exp_f32_e32 v242, v242
	v_exp_f32_e32 v243, v243
	v_pk_mul_f32 v[46:47], v[42:43], v[42:43]
	v_pk_add_f32 v[242:243], v[242:243], s[98:99] op_sel:[0,1] op_sel_hi:[1,1]
	v_pk_fma_f32 v[244:245], v[46:47], s[98:99], s[98:99] op_sel:[0,0,1] op_sel_hi:[1,0,1]
	v_pk_mul_f32 v[244:245], v[42:43], v[244:245]
	v_pk_mul_f32 v[244:245], v[244:245], s[100:101] op_sel_hi:[1,0]
	v_exp_f32_e32 v244, v244
	v_exp_f32_e32 v245, v245
	v_rcp_f32_e32 v56, v240
	v_rcp_f32_e32 v57, v241
	v_rcp_f32_e32 v55, v239
	v_rcp_f32_e32 v44, v242
	v_pk_add_f32 v[244:245], v[244:245], s[98:99] op_sel:[0,1] op_sel_hi:[1,1]
	v_rcp_f32_e32 v46, v244
	v_rcp_f32_e32 v47, v245
	v_rcp_f32_e32 v45, v243
	v_pk_mul_f32 v[50:51], v[50:51], v[54:55]
	v_ashrrev_i32_e32 v49, 31, v48
	v_pk_mul_f32 v[32:33], v[32:33], v[50:51]
	v_pk_mul_f32 v[42:43], v[42:43], v[46:47]
	v_pk_mul_f32 v[40:41], v[40:41], v[44:45]
	v_pk_mul_f32 v[42:43], v[26:27], v[42:43]
	v_pk_mul_f32 v[26:27], v[24:25], v[40:41]
	v_cvt_pk_bf16_f32 v24, v32, v33
	v_lshlrev_b64 v[32:33], 13, v[48:49]
	v_lshl_add_u64 v[32:33], s[44:45], 0, v[32:33]
	v_pk_mul_f32 v[52:53], v[52:53], v[56:57]
	v_lshl_add_u64 v[32:33], v[176:177], 1, v[32:33]
	v_pk_mul_f32 v[34:35], v[34:35], v[52:53]
	s_nop 0
	v_cvt_pk_bf16_f32 v25, v34, v35
	v_cvt_pk_bf16_f32 v26, v26, v27
	v_cvt_pk_bf16_f32 v27, v42, v43
	global_store_dwordx4 v[32:33], v[24:27], off nt

; __device__ __forceinline__ unsigned cvt_pk_bf16(float lo, float hi) { unsigned r; asm volatile("v_cvt_pk_bf16_f32 %0, %1, %2" : "=v"(r) : "v"(lo), "v"(hi)); return r; }
; __device__ __forceinline__ float dpp_ror1(float v) { return __builtin_bit_cast(float, __builtin_amdgcn_update_dpp(0, __builtin_bit_cast(int, v), 0x121, 0xf, 0xf, false)); }
; __device__ __forceinline__ float dpp_ror15(float v) { return __builtin_bit_cast(float, __builtin_amdgcn_update_dpp(0, __builtin_bit_cast(int, v), 0x12F, 0xf, 0xf, false)); }
;     __device__ __forceinline__ void operator()(const f32x4 (&acc)[2][2][4][2], const Unit& u, int wr, int wc, int fr, int fq) const {
;     ...
;                 f32x4 res[2];
;                 const float fzp = zp ? 0.f : 1.f, fzn = zn ? 0.f : 1.f;
; #pragma unroll
;                 for (int n = 0; n < 2; ++n) {
;                     const f32x4 g = acc[ai][0][m][n], up = acc[ai][1][m][n];
;                     f32x4 tp = g, tn = g;
;                     if (!fix) { const f32x4 gm = (m > 0) ? acc[ai][0][m - 1][n] : acc[ai ^ 1][0][3][n], gx = (m < 3) ? acc[ai][0][m + 1][n] : acc[ai ^ 1][0][0][n];
;                         tp = (fr == 15) ? gm : g; tn = (fr == 0) ? gx : g; }
;                     f32x4 gp, gn;
; #pragma unroll
;                     for (int j = 0; j < 4; ++j) { gp[j] = dpp_ror1(tp[j]); gn[j] = dpp_ror15(tn[j]); }
;                     const f32x4 cv = (w0[n] * fzp) * gp + (w1[n] * g + ((w2[n] * fzn) * gn + bb[n]));
;                     const f32x4 inner = cv * (cv * cv * 0.044715f + 1.0f) * (-2.0f * 0.7978845608028654f * 1.4426950408889634f);
;                     f32x4 sg;
; #pragma unroll
;                     for (int j = 0; j < 4; ++j) sg[j] = __builtin_amdgcn_rcpf(1.0f + __builtin_amdgcn_exp2f(inner[j]));
;                     res[n] = cv * sg * up;
;                 }
;                 if (valid) { u32x4 w; w.x = cvt_pk_bf16(res[0][0], res[0][1]); w.y = cvt_pk_bf16(res[0][2], res[0][3]); w.z = cvt_pk_bf16(res[1][0], res[1][1]); w.w = cvt_pk_bf16(res[1][2], res[1][3]);
;                     __builtin_nontemporal_store(w, (u32x4*)(ACT + (size_t)grow * 4096 + ch0)); }
.LBB0_685:
	v_cndmask_b32_e64 v33, v14, v38, s[18:19]
	v_cndmask_b32_e64 v27, v12, v36, s[18:19]
	v_cndmask_b32_e64 v23, v15, v23, s[16:17]
	v_mov_b32_dpp v36, v33 row_ror:15 row_mask:0xf bank_mask:0xf
	v_cndmask_b32_e64 v21, v13, v21, s[16:17]
	v_cndmask_b32_e64 v20, v12, v20, s[16:17]
	v_mov_b32_dpp v33, v23 row_ror:1 row_mask:0xf bank_mask:0xf
	v_cndmask_b32_e64 v23, v11, v19, s[16:17]
	v_cndmask_b32_e64 v19, v10, v18, s[16:17]
	v_cndmask_b32_e64 v18, v9, v17, s[16:17]
	v_cndmask_b32_e64 v17, v8, v16, s[16:17]
	v_cndmask_b32_e64 v32, v13, v37, s[18:19]
	v_mov_b32_dpp v34, v27 row_ror:15 row_mask:0xf bank_mask:0xf
	v_mov_b32_dpp v16, v17 row_ror:1 row_mask:0xf bank_mask:0xf
	v_cndmask_b32_e64 v22, v14, v22, s[16:17]
	v_mov_b32_dpp v26, v20 row_ror:1 row_mask:0xf bank_mask:0xf
	v_mov_b32_dpp v27, v21 row_ror:1 row_mask:0xf bank_mask:0xf
	v_mov_b32_dpp v35, v32 row_ror:15 row_mask:0xf bank_mask:0xf
	v_cndmask_b32_e64 v21, v8, v28, s[18:19]
	v_mov_b32_dpp v17, v18 row_ror:1 row_mask:0xf bank_mask:0xf
	v_cndmask_b32_e64 v25, v15, v39, s[18:19]
	v_mov_b32_dpp v32, v22 row_ror:1 row_mask:0xf bank_mask:0xf
	v_cndmask_b32_e64 v22, v9, v29, s[18:19]
	v_mov_b32_dpp v20, v21 row_ror:15 row_mask:0xf bank_mask:0xf
	v_mov_b32_dpp v18, v19 row_ror:1 row_mask:0xf bank_mask:0xf
	v_mov_b32_dpp v37, v25 row_ror:15 row_mask:0xf bank_mask:0xf
	v_cndmask_b32_e64 v25, v11, v31, s[18:19]
	v_cndmask_b32_e64 v30, v10, v30, s[18:19]
	v_mov_b32_dpp v21, v22 row_ror:15 row_mask:0xf bank_mask:0xf
	v_mov_b32_dpp v19, v23 row_ror:1 row_mask:0xf bank_mask:0xf
	v_mov_b32_dpp v22, v30 row_ror:15 row_mask:0xf bank_mask:0xf
	s_nop 0
	v_mov_b32_dpp v23, v25 row_ror:15 row_mask:0xf bank_mask:0xf
	s_and_saveexec_b64 s[16:17], s[20:21]
	s_cbranch_execz .LBB0_687
	v_pk_fma_f32 v[30:31], v[96:97], v[34:35], v[100:101]
	v_pk_fma_f32 v[28:29], v[98:99], v[36:37], v[102:103]
	v_pk_fma_f32 v[12:13], v[12:13], v[92:93], v[30:31]
	v_pk_fma_f32 v[14:15], v[14:15], v[94:95], v[28:29]
	v_pk_fma_f32 v[12:13], v[88:89], v[26:27], v[12:13]
	v_pk_fma_f32 v[14:15], v[90:91], v[32:33], v[14:15]
	v_pk_mul_f32 v[26:27], v[12:13], v[12:13]
	v_pk_fma_f32 v[238:239], v[26:27], s[98:99], s[98:99] op_sel:[0,0,1] op_sel_hi:[1,0,1]
	v_pk_mul_f32 v[238:239], v[12:13], v[238:239]
	v_pk_mul_f32 v[238:239], v[238:239], s[100:101] op_sel_hi:[1,0]
	v_exp_f32_e32 v238, v238
	v_exp_f32_e32 v239, v239
	v_pk_fma_f32 v[22:23], v[82:83], v[22:23], v[86:87]
	v_pk_add_f32 v[238:239], v[238:239], s[98:99] op_sel:[0,1] op_sel_hi:[1,1]
	v_pk_fma_f32 v[20:21], v[80:81], v[20:21], v[84:85]
	v_pk_mul_f32 v[28:29], v[14:15], v[14:15]
	v_pk_fma_f32 v[240:241], v[28:29], s[98:99], s[98:99] op_sel:[0,0,1] op_sel_hi:[1,0,1]
	v_pk_mul_f32 v[240:241], v[14:15], v[240:241]
	v_pk_mul_f32 v[240:241], v[240:241], s[100:101] op_sel_hi:[1,0]
	v_exp_f32_e32 v240, v240
	v_exp_f32_e32 v241, v241
	v_pk_fma_f32 v[8:9], v[8:9], v[76:77], v[20:21]
	v_pk_add_f32 v[240:241], v[240:241], s[98:99] op_sel:[0,1] op_sel_hi:[1,1]
	v_pk_fma_f32 v[10:11], v[10:11], v[78:79], v[22:23]
	v_rcp_f32_e32 v26, v238
	v_pk_fma_f32 v[8:9], v[72:73], v[16:17], v[8:9]
	v_pk_fma_f32 v[10:11], v[74:75], v[18:19], v[10:11]
	v_pk_mul_f32 v[16:17], v[8:9], v[8:9]
	v_pk_fma_f32 v[242:243], v[16:17], s[98:99], s[98:99] op_sel:[0,0,1] op_sel_hi:[1,0,1]
	v_pk_mul_f32 v[242:243], v[8:9], v[242:243]
	v_pk_mul_f32 v[242:243], v[242:243], s[100:101] op_sel_hi:[1,0]
	v_exp_f32_e32 v242, v242
	v_exp_f32_e32 v243, v243
	v_pk_mul_f32 v[18:19], v[10:11], v[10:11]
	v_pk_add_f32 v[242:243], v[242:243], s[98:99] op_sel:[0,1] op_sel_hi:[1,1]
	v_pk_fma_f32 v[244:245], v[18:19], s[98:99], s[98:99] op_sel:[0,0,1] op_sel_hi:[1,0,1]
	v_pk_mul_f32 v[244:245], v[10:11], v[244:245]
	v_pk_mul_f32 v[244:245], v[244:245], s[100:101] op_sel_hi:[1,0]
	v_exp_f32_e32 v244, v244
	v_exp_f32_e32 v245, v245
	v_rcp_f32_e32 v28, v240
	v_rcp_f32_e32 v29, v241
	v_rcp_f32_e32 v27, v239
	v_rcp_f32_e32 v16, v242
	v_pk_add_f32 v[244:245], v[244:245], s[98:99] op_sel:[0,1] op_sel_hi:[1,1]
	v_rcp_f32_e32 v18, v244
	v_rcp_f32_e32 v19, v245
	v_rcp_f32_e32 v17, v243
	v_pk_mul_f32 v[12:13], v[12:13], v[26:27]
	v_ashrrev_i32_e32 v25, 31, v24
	v_pk_mul_f32 v[4:5], v[4:5], v[12:13]
	v_pk_mul_f32 v[10:11], v[10:11], v[18:19]
	v_pk_mul_f32 v[8:9], v[8:9], v[16:17]
	v_pk_mul_f32 v[10:11], v[2:3], v[10:11]
	v_pk_mul_f32 v[2:3], v[0:1], v[8:9]
	v_cvt_pk_bf16_f32 v0, v4, v5
	v_lshlrev_b64 v[4:5], 13, v[24:25]
	v_lshl_add_u64 v[4:5], s[44:45], 0, v[4:5]
	v_pk_mul_f32 v[14:15], v[14:15], v[28:29]
	v_lshl_add_u64 v[4:5], v[176:177], 1, v[4:5]
	v_pk_mul_f32 v[6:7], v[6:7], v[14:15]
	s_nop 0
	v_cvt_pk_bf16_f32 v1, v6, v7
	v_cvt_pk_bf16_f32 v2, v2, v3
	v_cvt_pk_bf16_f32 v3, v10, v11
	global_store_dwordx4 v[4:5], v[0:3], off nt
